# peer gathers: 32-bit offsets + SGPR base; peer_act: LDS-DMA software pipelining
# speedup vs baseline: 1.0409x; 1.0081x over previous
.LBB0_633:
	s_or_b64 exec, exec, s[2:3]
	s_lshr_b32 s2, s88, 1
	s_and_b32 s2, s2, 0x7ffffffc
	v_add_u32_e32 v174, s2, v148
	s_lshr_b32 s2, s96, 1
	s_and_b32 s68, s2, 0x7ffffffc
	s_add_u32 s8, s94, 0x38700000
	v_readlane_b32 s4, v252, 27
	s_addc_u32 s9, s95, 0
	s_lshl_b32 s35, s4, 21
	v_and_b32_e32 v211, 7, v156
	s_add_u32 s2, s8, s35
	s_addc_u32 s3, s9, 0
	v_lshlrev_b32_e32 v186, 4, v211
	v_mov_b32_e32 v187, 0
	v_lshl_add_u64 v[178:179], s[2:3], 0, v[186:187]
	s_mul_i32 s2, s4, 0x2040000
	s_add_u32 s46, s0, s2
	s_mov_b32 s14, 0x10200
	v_lshrrev_b32_e32 v210, 3, v154
	s_mov_b32 s5, 0
	s_addc_u32 s47, s1, 0
	v_cmp_gt_i32_e64 s[12:13], s14, v174
	v_ashrrev_i32_e32 v175, 31, v174
	v_add_u32_e32 v176, s68, v174
	v_lshlrev_b32_e32 v182, 1, v186
	v_lshlrev_b32_e32 v172, 2, v154
	s_mul_i32 s69, s33, 12
	s_barrier
	s_and_saveexec_b64 s[2:3], s[12:13]
	s_cbranch_execz .LBB0_648
	s_waitcnt vmcnt(5)
	v_lshlrev_b64 v[0:1], 9, v[174:175]
	v_lshl_add_u64 v[0:1], s[38:39], 0, v[0:1]
	v_mov_b32_e32 v173, v187
	v_lshl_add_u64 v[0:1], v[0:1], 0, v[172:173]
	global_load_dword v161, v[0:1], off
	global_load_dword v163, v[0:1], off offset:256
	v_lshlrev_b64 v[0:1], 11, v[174:175]
	v_readlane_b32 s15, v252, 27
	s_lshl_b32 s4, s15, 8
	v_mbcnt_hi_u32_b32 v2, -1, v155
	v_lshl_add_u64 v[0:1], s[94:95], 0, v[0:1]
	v_mov_b32_e32 v183, v187
	v_and_or_b32 v2, v2, 64, v210
	v_lshl_add_u64 v[0:1], v[0:1], 0, s[4:5]
	v_lshlrev_b32_e32 v159, 2, v2
	v_lshl_add_u64 v[0:1], v[0:1], 0, v[182:183]
	global_load_dwordx4 v[144:147], v[0:1], off offset:16
	global_load_dwordx4 v[148:151], v[0:1], off
	s_lshl_b32 s16, s15, 7
	v_cmp_gt_i32_e32 vcc, s14, v176
	v_and_b32_e32 v255, 7, v156
	v_lshlrev_b32_e32 v255, 4, v255
	v_readfirstlane_b32 s98, v178
	v_readfirstlane_b32 s99, v179
	s_waitcnt vmcnt(3)
	ds_bpermute_b32 v0, v159, v161
	ds_bpermute_b32 v2, v159, v161 offset:32
	ds_bpermute_b32 v4, v159, v161 offset:64
	ds_bpermute_b32 v6, v159, v161 offset:96
	ds_bpermute_b32 v8, v159, v161 offset:128
	ds_bpermute_b32 v10, v159, v161 offset:160
	ds_bpermute_b32 v12, v159, v161 offset:192
	ds_bpermute_b32 v14, v159, v161 offset:224
	s_waitcnt vmcnt(2)
	ds_bpermute_b32 v16, v159, v163
	ds_bpermute_b32 v18, v159, v163 offset:32
	ds_bpermute_b32 v20, v159, v163 offset:64
	ds_bpermute_b32 v22, v159, v163 offset:96
	ds_bpermute_b32 v24, v159, v163 offset:128
	ds_bpermute_b32 v26, v159, v163 offset:160
	ds_bpermute_b32 v28, v159, v163 offset:192
	s_waitcnt lgkmcnt(14)
	s_waitcnt lgkmcnt(13)
	s_waitcnt lgkmcnt(12)
	s_waitcnt lgkmcnt(11)
	s_waitcnt lgkmcnt(10)
	s_waitcnt lgkmcnt(9)
	s_waitcnt lgkmcnt(8)
	s_waitcnt lgkmcnt(7)
	s_waitcnt lgkmcnt(6)
	s_waitcnt lgkmcnt(5)
	s_waitcnt lgkmcnt(4)
	s_waitcnt lgkmcnt(3)
	s_waitcnt lgkmcnt(2)
	s_waitcnt lgkmcnt(1)
	s_waitcnt lgkmcnt(0)
	v_lshl_add_u32 v0, v0, 7, v255
	v_lshl_add_u32 v30, v2, 7, v255
	v_lshl_add_u32 v32, v4, 7, v255
	v_lshl_add_u32 v34, v6, 7, v255
	v_lshl_add_u32 v36, v8, 7, v255
	v_lshl_add_u32 v38, v10, 7, v255
	v_lshl_add_u32 v40, v12, 7, v255
	v_lshl_add_u32 v42, v14, 7, v255
	v_lshl_add_u32 v44, v16, 7, v255
	v_lshl_add_u32 v46, v18, 7, v255
	v_lshl_add_u32 v48, v20, 7, v255
	v_lshl_add_u32 v50, v22, 7, v255
	v_lshl_add_u32 v52, v24, 7, v255
	v_lshl_add_u32 v54, v26, 7, v255
	v_lshl_add_u32 v58, v28, 7, v255
	global_load_dwordx4 v[0:3], v0, s[98:99]
	s_nop 0
	global_load_dwordx4 v[4:7], v30, s[98:99]
	global_load_dwordx4 v[8:11], v32, s[98:99]
	global_load_dwordx4 v[12:15], v34, s[98:99]
	global_load_dwordx4 v[16:19], v36, s[98:99]
	global_load_dwordx4 v[20:23], v38, s[98:99]
	global_load_dwordx4 v[24:27], v40, s[98:99]
	global_load_dwordx4 v[28:31], v42, s[98:99]
	s_nop 0
	global_load_dwordx4 v[32:35], v44, s[98:99]
	global_load_dwordx4 v[36:39], v46, s[98:99]
	global_load_dwordx4 v[40:43], v48, s[98:99]
	s_nop 0
	global_load_dwordx4 v[44:47], v50, s[98:99]
	s_nop 0
	global_load_dwordx4 v[48:51], v52, s[98:99]
	s_nop 0
	global_load_dwordx4 v[52:55], v54, s[98:99]
	ds_bpermute_b32 v56, v159, v163 offset:224
	s_waitcnt lgkmcnt(0)
	v_lshl_add_u32 v60, v56, 7, v255
	global_load_dwordx4 v[56:59], v58, s[98:99]
	s_nop 0
	global_load_dwordx4 v[60:63], v60, s[98:99]
	s_and_saveexec_b64 s[14:15], vcc
	s_cbranch_execz .LBB0_636
	v_ashrrev_i32_e32 v177, 31, v176
	v_lshlrev_b64 v[64:65], 11, v[176:177]
	v_lshl_add_u64 v[64:65], s[94:95], 0, v[64:65]
	s_lshl_b32 s4, s16, 1
	v_lshl_add_u64 v[64:65], v[64:65], 0, s[4:5]
	v_mov_b32_e32 v183, 0
	v_lshl_add_u64 v[64:65], v[64:65], 0, v[182:183]
	global_load_dwordx4 v[136:139], v[64:65], off offset:16
	global_load_dwordx4 v[140:143], v[64:65], off
	v_lshlrev_b64 v[64:65], 9, v[176:177]
	v_lshl_add_u64 v[64:65], s[38:39], 0, v[64:65]
	v_mov_b32_e32 v173, v183
	v_lshl_add_u64 v[64:65], v[64:65], 0, v[172:173]
	global_load_dword v177, v[64:65], off
	global_load_dword v213, v[64:65], off offset:256

.LBB0_639:
	v_add_u32_e32 v192, s68, v190
	v_cmp_gt_i32_e64 s[28:29], s53, v192
	s_and_saveexec_b64 s[30:31], s[28:29]
	s_cbranch_execz .LBB0_641
	s_waitcnt vmcnt(1)
	ds_bpermute_b32 v64, v159, v177
	ds_bpermute_b32 v66, v187, v177
	ds_bpermute_b32 v72, v212, v177
	ds_bpermute_b32 v74, v214, v177
	ds_bpermute_b32 v80, v215, v177
	ds_bpermute_b32 v82, v216, v177
	ds_bpermute_b32 v88, v217, v177
	ds_bpermute_b32 v90, v218, v177
	s_waitcnt vmcnt(0)
	ds_bpermute_b32 v96, v159, v213
	ds_bpermute_b32 v98, v187, v213
	ds_bpermute_b32 v104, v212, v213
	ds_bpermute_b32 v106, v214, v213
	ds_bpermute_b32 v112, v215, v213
	ds_bpermute_b32 v114, v216, v213
	ds_bpermute_b32 v120, v217, v213
	ds_bpermute_b32 v122, v218, v213
	s_waitcnt lgkmcnt(14)
	s_waitcnt lgkmcnt(13)
	s_waitcnt lgkmcnt(12)
	s_waitcnt lgkmcnt(11)
	s_waitcnt lgkmcnt(10)
	s_waitcnt lgkmcnt(9)
	s_waitcnt lgkmcnt(8)
	s_waitcnt lgkmcnt(7)
	s_waitcnt lgkmcnt(6)
	s_waitcnt lgkmcnt(5)
	s_waitcnt lgkmcnt(4)
	s_waitcnt lgkmcnt(3)
	s_waitcnt lgkmcnt(2)
	s_waitcnt lgkmcnt(1)
	s_waitcnt lgkmcnt(0)
	v_lshl_add_u32 v64, v64, 7, v255
	v_lshl_add_u32 v66, v66, 7, v255
	v_lshl_add_u32 v72, v72, 7, v255
	v_lshl_add_u32 v74, v74, 7, v255
	v_lshl_add_u32 v80, v80, 7, v255
	v_lshl_add_u32 v82, v82, 7, v255
	v_lshl_add_u32 v88, v88, 7, v255
	v_lshl_add_u32 v90, v90, 7, v255
	v_lshl_add_u32 v96, v96, 7, v255
	v_lshl_add_u32 v98, v98, 7, v255
	v_lshl_add_u32 v104, v104, 7, v255
	v_lshl_add_u32 v106, v106, 7, v255
	v_lshl_add_u32 v112, v112, 7, v255
	v_lshl_add_u32 v114, v114, 7, v255
	v_lshl_add_u32 v120, v120, 7, v255
	v_lshl_add_u32 v122, v122, 7, v255
	global_load_dwordx4 v[68:71], v64, s[98:99]
	s_nop 0
	global_load_dwordx4 v[64:67], v66, s[98:99]
	s_nop 0
	global_load_dwordx4 v[76:79], v72, s[98:99]
	s_nop 0
	global_load_dwordx4 v[72:75], v74, s[98:99]
	s_nop 0
	global_load_dwordx4 v[84:87], v80, s[98:99]
	s_nop 0
	global_load_dwordx4 v[80:83], v82, s[98:99]
	s_nop 0
	global_load_dwordx4 v[92:95], v88, s[98:99]
	s_nop 0
	global_load_dwordx4 v[88:91], v90, s[98:99]
	s_nop 0
	global_load_dwordx4 v[100:103], v96, s[98:99]
	s_nop 0
	global_load_dwordx4 v[96:99], v98, s[98:99]
	s_nop 0
	global_load_dwordx4 v[108:111], v104, s[98:99]
	s_nop 0
	global_load_dwordx4 v[104:107], v106, s[98:99]
	s_nop 0
	global_load_dwordx4 v[116:119], v112, s[98:99]
	s_nop 0
	global_load_dwordx4 v[112:115], v114, s[98:99]
	s_nop 0
	global_load_dwordx4 v[124:127], v120, s[98:99]
	s_nop 0
	global_load_dwordx4 v[120:123], v122, s[98:99]

.LBB0_643:
	s_or_b64 exec, exec, s[48:49]
	v_lshlrev_b32_e32 v200, 16, v148
	v_and_b32_e32 v201, 0xffff0000, v148
	v_lshlrev_b32_e32 v202, 16, v149
	v_and_b32_e32 v203, 0xffff0000, v149
	v_lshlrev_b32_e32 v198, 16, v150
	v_and_b32_e32 v199, 0xffff0000, v150
	v_lshlrev_b32_e32 v194, 16, v151
	v_and_b32_e32 v195, 0xffff0000, v151
	v_lshlrev_b32_e32 v196, 16, v144
	v_and_b32_e32 v197, 0xffff0000, v144
	v_lshlrev_b32_e32 v150, 16, v145
	v_and_b32_e32 v151, 0xffff0000, v145
	v_lshlrev_b32_e32 v148, 16, v146
	v_and_b32_e32 v149, 0xffff0000, v146
	v_lshlrev_b32_e32 v144, 16, v147
	v_and_b32_e32 v145, 0xffff0000, v147
	s_waitcnt vmcnt(15)
	v_cvt_pk_f32_fp8_sdwa v[220:221], v0 src0_sel:WORD_1
	v_cvt_pk_f32_fp8_e32 v[146:147], v0
	s_waitcnt vmcnt(7)
	v_cvt_pk_f32_fp8_sdwa v[222:223], v32 src0_sel:WORD_1
	v_ashrrev_i32_e32 v191, 31, v190
	v_pk_mul_f32 v[220:221], v[220:221], v[202:203]
	s_mov_b64 s[50:51], -1
	v_pk_fma_f32 v[146:147], v[146:147], v[200:201], v[220:221]
	v_cvt_pk_f32_fp8_e32 v[220:221], v1
	v_pk_mul_f32 v[222:223], v[222:223], v[202:203]
	v_pk_fma_f32 v[146:147], v[220:221], v[198:199], v[146:147]
	v_cvt_pk_f32_fp8_sdwa v[220:221], v1 src0_sel:WORD_1
	v_pk_fma_f32 v[146:147], v[220:221], v[194:195], v[146:147]
	v_cvt_pk_f32_fp8_e32 v[220:221], v2
	v_pk_fma_f32 v[146:147], v[220:221], v[196:197], v[146:147]
	v_cvt_pk_f32_fp8_sdwa v[220:221], v2 src0_sel:WORD_1
	v_pk_fma_f32 v[146:147], v[220:221], v[150:151], v[146:147]
	v_cvt_pk_f32_fp8_e32 v[220:221], v3
	v_pk_fma_f32 v[146:147], v[220:221], v[148:149], v[146:147]
	v_cvt_pk_f32_fp8_sdwa v[220:221], v3 src0_sel:WORD_1
	v_pk_fma_f32 v[146:147], v[220:221], v[144:145], v[146:147]
	s_nop 0
	v_add_f32_e32 v146, v146, v147
	v_cvt_pk_f32_fp8_sdwa v[220:221], v4 src0_sel:WORD_1
	v_pk_mul_f32 v[220:221], v[220:221], v[202:203]
	v_add_f32_dpp v146, v146, v146 quad_perm:[1,0,3,2] row_mask:0xf bank_mask:0xf bound_ctrl:1
	s_nop 1
	v_add_f32_dpp v146, v146, v146 quad_perm:[2,3,0,1] row_mask:0xf bank_mask:0xf bound_ctrl:1
	s_nop 1
	v_add_f32_dpp v146, v146, v146 row_half_mirror row_mask:0xf bank_mask:0xf bound_ctrl:1
	v_cndmask_b32_e32 v173, 0, v146, vcc
	v_cvt_pk_f32_fp8_e32 v[146:147], v4
	v_pk_fma_f32 v[146:147], v[146:147], v[200:201], v[220:221]
	v_cvt_pk_f32_fp8_e32 v[220:221], v5
	v_pk_fma_f32 v[146:147], v[220:221], v[198:199], v[146:147]
	v_cvt_pk_f32_fp8_sdwa v[220:221], v5 src0_sel:WORD_1
	v_pk_fma_f32 v[146:147], v[220:221], v[194:195], v[146:147]
	v_cvt_pk_f32_fp8_e32 v[220:221], v6
	v_pk_fma_f32 v[146:147], v[220:221], v[196:197], v[146:147]
	v_cvt_pk_f32_fp8_sdwa v[220:221], v6 src0_sel:WORD_1
	v_pk_fma_f32 v[146:147], v[220:221], v[150:151], v[146:147]
	v_cvt_pk_f32_fp8_e32 v[220:221], v7
	v_pk_fma_f32 v[146:147], v[220:221], v[148:149], v[146:147]
	v_cvt_pk_f32_fp8_sdwa v[220:221], v7 src0_sel:WORD_1
	v_pk_fma_f32 v[146:147], v[220:221], v[144:145], v[146:147]
	s_nop 0
	v_add_f32_e32 v146, v146, v147
	v_cvt_pk_f32_fp8_sdwa v[220:221], v8 src0_sel:WORD_1
	v_pk_mul_f32 v[220:221], v[220:221], v[202:203]
	v_add_f32_dpp v146, v146, v146 quad_perm:[1,0,3,2] row_mask:0xf bank_mask:0xf bound_ctrl:1
	s_nop 1
	v_add_f32_dpp v146, v146, v146 quad_perm:[2,3,0,1] row_mask:0xf bank_mask:0xf bound_ctrl:1
	s_nop 1
	v_add_f32_dpp v146, v146, v146 row_half_mirror row_mask:0xf bank_mask:0xf bound_ctrl:1
	v_cndmask_b32_e64 v173, v173, v146, s[14:15]
	v_cvt_pk_f32_fp8_e32 v[146:147], v8
	v_pk_fma_f32 v[146:147], v[146:147], v[200:201], v[220:221]
	v_cvt_pk_f32_fp8_e32 v[220:221], v9
	v_pk_fma_f32 v[146:147], v[220:221], v[198:199], v[146:147]
	v_cvt_pk_f32_fp8_sdwa v[220:221], v9 src0_sel:WORD_1
	v_pk_fma_f32 v[146:147], v[220:221], v[194:195], v[146:147]
	v_cvt_pk_f32_fp8_e32 v[220:221], v10
	v_pk_fma_f32 v[146:147], v[220:221], v[196:197], v[146:147]
	v_cvt_pk_f32_fp8_sdwa v[220:221], v10 src0_sel:WORD_1
	v_pk_fma_f32 v[146:147], v[220:221], v[150:151], v[146:147]
	v_cvt_pk_f32_fp8_e32 v[220:221], v11
	v_pk_fma_f32 v[146:147], v[220:221], v[148:149], v[146:147]
	v_cvt_pk_f32_fp8_sdwa v[220:221], v11 src0_sel:WORD_1
	v_pk_fma_f32 v[146:147], v[220:221], v[144:145], v[146:147]
	s_nop 0
	v_add_f32_e32 v146, v146, v147
	v_cvt_pk_f32_fp8_sdwa v[220:221], v12 src0_sel:WORD_1
	v_pk_mul_f32 v[220:221], v[220:221], v[202:203]
	v_add_f32_dpp v146, v146, v146 quad_perm:[1,0,3,2] row_mask:0xf bank_mask:0xf bound_ctrl:1
	s_nop 1
	v_add_f32_dpp v146, v146, v146 quad_perm:[2,3,0,1] row_mask:0xf bank_mask:0xf bound_ctrl:1
	s_nop 1
	v_add_f32_dpp v146, v146, v146 row_half_mirror row_mask:0xf bank_mask:0xf bound_ctrl:1
	v_cndmask_b32_e64 v173, v173, v146, s[16:17]
	v_cvt_pk_f32_fp8_e32 v[146:147], v12
	v_pk_fma_f32 v[146:147], v[146:147], v[200:201], v[220:221]
	v_cvt_pk_f32_fp8_e32 v[220:221], v13
	v_pk_fma_f32 v[146:147], v[220:221], v[198:199], v[146:147]
	v_cvt_pk_f32_fp8_sdwa v[220:221], v13 src0_sel:WORD_1
	v_pk_fma_f32 v[146:147], v[220:221], v[194:195], v[146:147]
	v_cvt_pk_f32_fp8_e32 v[220:221], v14
	v_pk_fma_f32 v[146:147], v[220:221], v[196:197], v[146:147]
	v_cvt_pk_f32_fp8_sdwa v[220:221], v14 src0_sel:WORD_1
	v_pk_fma_f32 v[146:147], v[220:221], v[150:151], v[146:147]
	v_cvt_pk_f32_fp8_e32 v[220:221], v15
	v_pk_fma_f32 v[146:147], v[220:221], v[148:149], v[146:147]
	v_cvt_pk_f32_fp8_sdwa v[220:221], v15 src0_sel:WORD_1
	v_pk_fma_f32 v[146:147], v[220:221], v[144:145], v[146:147]
	s_nop 0
	v_add_f32_e32 v146, v146, v147
	v_cvt_pk_f32_fp8_sdwa v[220:221], v16 src0_sel:WORD_1
	v_pk_mul_f32 v[220:221], v[220:221], v[202:203]
	v_add_f32_dpp v146, v146, v146 quad_perm:[1,0,3,2] row_mask:0xf bank_mask:0xf bound_ctrl:1
	s_nop 1
	v_add_f32_dpp v146, v146, v146 quad_perm:[2,3,0,1] row_mask:0xf bank_mask:0xf bound_ctrl:1
	s_nop 1
	v_add_f32_dpp v146, v146, v146 row_half_mirror row_mask:0xf bank_mask:0xf bound_ctrl:1
	v_cndmask_b32_e64 v173, v173, v146, s[18:19]
	v_cvt_pk_f32_fp8_e32 v[146:147], v16
	v_pk_fma_f32 v[146:147], v[146:147], v[200:201], v[220:221]
	v_cvt_pk_f32_fp8_e32 v[220:221], v17
	v_pk_fma_f32 v[146:147], v[220:221], v[198:199], v[146:147]
	v_cvt_pk_f32_fp8_sdwa v[220:221], v17 src0_sel:WORD_1
	v_pk_fma_f32 v[146:147], v[220:221], v[194:195], v[146:147]
	v_cvt_pk_f32_fp8_e32 v[220:221], v18
	v_pk_fma_f32 v[146:147], v[220:221], v[196:197], v[146:147]
	v_cvt_pk_f32_fp8_sdwa v[220:221], v18 src0_sel:WORD_1
	v_pk_fma_f32 v[146:147], v[220:221], v[150:151], v[146:147]
	v_cvt_pk_f32_fp8_e32 v[220:221], v19
	v_pk_fma_f32 v[146:147], v[220:221], v[148:149], v[146:147]
	v_cvt_pk_f32_fp8_sdwa v[220:221], v19 src0_sel:WORD_1
	v_pk_fma_f32 v[146:147], v[220:221], v[144:145], v[146:147]
	s_nop 0
	v_add_f32_e32 v146, v146, v147
	v_cvt_pk_f32_fp8_sdwa v[220:221], v20 src0_sel:WORD_1
	v_pk_mul_f32 v[220:221], v[220:221], v[202:203]
	v_add_f32_dpp v146, v146, v146 quad_perm:[1,0,3,2] row_mask:0xf bank_mask:0xf bound_ctrl:1
	s_nop 1
	v_add_f32_dpp v146, v146, v146 quad_perm:[2,3,0,1] row_mask:0xf bank_mask:0xf bound_ctrl:1
	s_nop 1
	v_add_f32_dpp v146, v146, v146 row_half_mirror row_mask:0xf bank_mask:0xf bound_ctrl:1
	v_cndmask_b32_e64 v173, v173, v146, s[20:21]
	v_cvt_pk_f32_fp8_e32 v[146:147], v20
	v_pk_fma_f32 v[146:147], v[146:147], v[200:201], v[220:221]
	v_cvt_pk_f32_fp8_e32 v[220:221], v21
	v_pk_fma_f32 v[146:147], v[220:221], v[198:199], v[146:147]
	v_cvt_pk_f32_fp8_sdwa v[220:221], v21 src0_sel:WORD_1
	v_pk_fma_f32 v[146:147], v[220:221], v[194:195], v[146:147]
	v_cvt_pk_f32_fp8_e32 v[220:221], v22
	v_pk_fma_f32 v[146:147], v[220:221], v[196:197], v[146:147]
	v_cvt_pk_f32_fp8_sdwa v[220:221], v22 src0_sel:WORD_1
	v_pk_fma_f32 v[146:147], v[220:221], v[150:151], v[146:147]
	v_cvt_pk_f32_fp8_e32 v[220:221], v23
	v_pk_fma_f32 v[146:147], v[220:221], v[148:149], v[146:147]
	v_cvt_pk_f32_fp8_sdwa v[220:221], v23 src0_sel:WORD_1
	v_pk_fma_f32 v[146:147], v[220:221], v[144:145], v[146:147]
	s_nop 0
	v_add_f32_e32 v146, v146, v147
	v_cvt_pk_f32_fp8_sdwa v[220:221], v24 src0_sel:WORD_1
	v_pk_mul_f32 v[220:221], v[220:221], v[202:203]
	v_add_f32_dpp v146, v146, v146 quad_perm:[1,0,3,2] row_mask:0xf bank_mask:0xf bound_ctrl:1
	s_nop 1
	v_add_f32_dpp v146, v146, v146 quad_perm:[2,3,0,1] row_mask:0xf bank_mask:0xf bound_ctrl:1
	s_nop 1
	v_add_f32_dpp v146, v146, v146 row_half_mirror row_mask:0xf bank_mask:0xf bound_ctrl:1
	v_cndmask_b32_e64 v173, v173, v146, s[22:23]
	v_cvt_pk_f32_fp8_e32 v[146:147], v24
	v_pk_fma_f32 v[146:147], v[146:147], v[200:201], v[220:221]
	v_cvt_pk_f32_fp8_e32 v[220:221], v25
	v_pk_fma_f32 v[146:147], v[220:221], v[198:199], v[146:147]
	v_cvt_pk_f32_fp8_sdwa v[220:221], v25 src0_sel:WORD_1
	v_pk_fma_f32 v[146:147], v[220:221], v[194:195], v[146:147]
	v_cvt_pk_f32_fp8_e32 v[220:221], v26
	v_pk_fma_f32 v[146:147], v[220:221], v[196:197], v[146:147]
	v_cvt_pk_f32_fp8_sdwa v[220:221], v26 src0_sel:WORD_1
	v_pk_fma_f32 v[146:147], v[220:221], v[150:151], v[146:147]
	v_cvt_pk_f32_fp8_e32 v[220:221], v27
	v_pk_fma_f32 v[146:147], v[220:221], v[148:149], v[146:147]
	v_cvt_pk_f32_fp8_sdwa v[220:221], v27 src0_sel:WORD_1
	v_pk_fma_f32 v[146:147], v[220:221], v[144:145], v[146:147]
	s_nop 0
	v_add_f32_e32 v146, v146, v147
	v_cvt_pk_f32_fp8_sdwa v[220:221], v28 src0_sel:WORD_1
	v_pk_mul_f32 v[220:221], v[220:221], v[202:203]
	v_add_f32_dpp v146, v146, v146 quad_perm:[1,0,3,2] row_mask:0xf bank_mask:0xf bound_ctrl:1
	s_nop 1
	v_add_f32_dpp v146, v146, v146 quad_perm:[2,3,0,1] row_mask:0xf bank_mask:0xf bound_ctrl:1
	s_nop 1
	v_add_f32_dpp v146, v146, v146 row_half_mirror row_mask:0xf bank_mask:0xf bound_ctrl:1
	v_cndmask_b32_e64 v173, v173, v146, s[24:25]
	v_cvt_pk_f32_fp8_e32 v[146:147], v28
	v_pk_fma_f32 v[146:147], v[146:147], v[200:201], v[220:221]
	v_cvt_pk_f32_fp8_e32 v[220:221], v29
	v_pk_fma_f32 v[146:147], v[220:221], v[198:199], v[146:147]
	v_cvt_pk_f32_fp8_sdwa v[220:221], v29 src0_sel:WORD_1
	v_pk_fma_f32 v[146:147], v[220:221], v[194:195], v[146:147]
	v_cvt_pk_f32_fp8_e32 v[220:221], v30
	v_pk_fma_f32 v[146:147], v[220:221], v[196:197], v[146:147]
	v_cvt_pk_f32_fp8_sdwa v[220:221], v30 src0_sel:WORD_1
	v_pk_fma_f32 v[146:147], v[220:221], v[150:151], v[146:147]
	v_cvt_pk_f32_fp8_e32 v[220:221], v31
	v_pk_fma_f32 v[146:147], v[220:221], v[148:149], v[146:147]
	v_cvt_pk_f32_fp8_sdwa v[220:221], v31 src0_sel:WORD_1
	v_pk_fma_f32 v[146:147], v[220:221], v[144:145], v[146:147]
	v_cvt_pk_f32_fp8_e32 v[220:221], v32
	v_add_f32_e32 v146, v146, v147
	v_pk_fma_f32 v[220:221], v[220:221], v[200:201], v[222:223]
	v_cvt_pk_f32_fp8_e32 v[222:223], v33
	v_add_f32_dpp v146, v146, v146 quad_perm:[1,0,3,2] row_mask:0xf bank_mask:0xf bound_ctrl:1
	v_pk_fma_f32 v[220:221], v[222:223], v[198:199], v[220:221]
	v_cvt_pk_f32_fp8_sdwa v[222:223], v33 src0_sel:WORD_1
	v_add_f32_dpp v146, v146, v146 quad_perm:[2,3,0,1] row_mask:0xf bank_mask:0xf bound_ctrl:1
	v_pk_fma_f32 v[220:221], v[222:223], v[194:195], v[220:221]
	v_cvt_pk_f32_fp8_e32 v[222:223], v34
	v_add_f32_dpp v146, v146, v146 row_half_mirror row_mask:0xf bank_mask:0xf bound_ctrl:1
	v_cndmask_b32_e64 v146, v173, v146, s[26:27]
	v_pk_fma_f32 v[220:221], v[222:223], v[196:197], v[220:221]
	v_cvt_pk_f32_fp8_sdwa v[222:223], v34 src0_sel:WORD_1
	v_pk_fma_f32 v[220:221], v[222:223], v[150:151], v[220:221]
	v_cvt_pk_f32_fp8_e32 v[222:223], v35
	v_pk_fma_f32 v[220:221], v[222:223], v[148:149], v[220:221]
	v_cvt_pk_f32_fp8_sdwa v[222:223], v35 src0_sel:WORD_1
	v_pk_fma_f32 v[220:221], v[222:223], v[144:145], v[220:221]
	s_waitcnt vmcnt(6)
	v_cvt_pk_f32_fp8_sdwa v[222:223], v36 src0_sel:WORD_1
	v_add_f32_e32 v147, v220, v221
	v_cvt_pk_f32_fp8_e32 v[220:221], v36
	v_pk_mul_f32 v[222:223], v[222:223], v[202:203]
	v_add_f32_dpp v147, v147, v147 quad_perm:[1,0,3,2] row_mask:0xf bank_mask:0xf bound_ctrl:1
	v_pk_fma_f32 v[220:221], v[220:221], v[200:201], v[222:223]
	v_cvt_pk_f32_fp8_e32 v[222:223], v37
	v_add_f32_dpp v147, v147, v147 quad_perm:[2,3,0,1] row_mask:0xf bank_mask:0xf bound_ctrl:1
	v_pk_fma_f32 v[220:221], v[222:223], v[198:199], v[220:221]
	v_cvt_pk_f32_fp8_sdwa v[222:223], v37 src0_sel:WORD_1
	v_add_f32_dpp v147, v147, v147 row_half_mirror row_mask:0xf bank_mask:0xf bound_ctrl:1
	v_cndmask_b32_e32 v147, 0, v147, vcc
	v_pk_fma_f32 v[220:221], v[222:223], v[194:195], v[220:221]
	v_cvt_pk_f32_fp8_e32 v[222:223], v38
	v_pk_fma_f32 v[220:221], v[222:223], v[196:197], v[220:221]
	v_cvt_pk_f32_fp8_sdwa v[222:223], v38 src0_sel:WORD_1
	v_pk_fma_f32 v[220:221], v[222:223], v[150:151], v[220:221]
	v_cvt_pk_f32_fp8_e32 v[222:223], v39
	v_pk_fma_f32 v[220:221], v[222:223], v[148:149], v[220:221]
	v_cvt_pk_f32_fp8_sdwa v[222:223], v39 src0_sel:WORD_1
	v_pk_fma_f32 v[220:221], v[222:223], v[144:145], v[220:221]
	s_waitcnt vmcnt(5)
	v_cvt_pk_f32_fp8_sdwa v[222:223], v40 src0_sel:WORD_1
	v_add_f32_e32 v173, v220, v221
	v_cvt_pk_f32_fp8_e32 v[220:221], v40
	v_pk_mul_f32 v[222:223], v[222:223], v[202:203]
	v_add_f32_dpp v173, v173, v173 quad_perm:[1,0,3,2] row_mask:0xf bank_mask:0xf bound_ctrl:1
	v_pk_fma_f32 v[220:221], v[220:221], v[200:201], v[222:223]
	v_cvt_pk_f32_fp8_e32 v[222:223], v41
	v_add_f32_dpp v173, v173, v173 quad_perm:[2,3,0,1] row_mask:0xf bank_mask:0xf bound_ctrl:1
	v_pk_fma_f32 v[220:221], v[222:223], v[198:199], v[220:221]
	v_cvt_pk_f32_fp8_sdwa v[222:223], v41 src0_sel:WORD_1
	v_add_f32_dpp v173, v173, v173 row_half_mirror row_mask:0xf bank_mask:0xf bound_ctrl:1
	v_cndmask_b32_e64 v147, v147, v173, s[14:15]
	v_pk_fma_f32 v[220:221], v[222:223], v[194:195], v[220:221]
	v_cvt_pk_f32_fp8_e32 v[222:223], v42
	v_pk_fma_f32 v[220:221], v[222:223], v[196:197], v[220:221]
	v_cvt_pk_f32_fp8_sdwa v[222:223], v42 src0_sel:WORD_1
	v_pk_fma_f32 v[220:221], v[222:223], v[150:151], v[220:221]
	v_cvt_pk_f32_fp8_e32 v[222:223], v43
	v_pk_fma_f32 v[220:221], v[222:223], v[148:149], v[220:221]
	v_cvt_pk_f32_fp8_sdwa v[222:223], v43 src0_sel:WORD_1
	v_pk_fma_f32 v[220:221], v[222:223], v[144:145], v[220:221]
	s_waitcnt vmcnt(4)
	v_cvt_pk_f32_fp8_sdwa v[222:223], v44 src0_sel:WORD_1
	v_add_f32_e32 v173, v220, v221
	v_cvt_pk_f32_fp8_e32 v[220:221], v44
	v_pk_mul_f32 v[222:223], v[222:223], v[202:203]
	v_add_f32_dpp v173, v173, v173 quad_perm:[1,0,3,2] row_mask:0xf bank_mask:0xf bound_ctrl:1
	v_pk_fma_f32 v[220:221], v[220:221], v[200:201], v[222:223]
	v_cvt_pk_f32_fp8_e32 v[222:223], v45
	v_add_f32_dpp v173, v173, v173 quad_perm:[2,3,0,1] row_mask:0xf bank_mask:0xf bound_ctrl:1
	v_pk_fma_f32 v[220:221], v[222:223], v[198:199], v[220:221]
	v_cvt_pk_f32_fp8_sdwa v[222:223], v45 src0_sel:WORD_1
	v_add_f32_dpp v173, v173, v173 row_half_mirror row_mask:0xf bank_mask:0xf bound_ctrl:1
	v_cndmask_b32_e64 v147, v147, v173, s[16:17]
	v_pk_fma_f32 v[220:221], v[222:223], v[194:195], v[220:221]
	v_cvt_pk_f32_fp8_e32 v[222:223], v46
	v_pk_fma_f32 v[220:221], v[222:223], v[196:197], v[220:221]
	v_cvt_pk_f32_fp8_sdwa v[222:223], v46 src0_sel:WORD_1
	v_pk_fma_f32 v[220:221], v[222:223], v[150:151], v[220:221]
	v_cvt_pk_f32_fp8_e32 v[222:223], v47
	v_pk_fma_f32 v[220:221], v[222:223], v[148:149], v[220:221]
	v_cvt_pk_f32_fp8_sdwa v[222:223], v47 src0_sel:WORD_1
	v_pk_fma_f32 v[220:221], v[222:223], v[144:145], v[220:221]
	s_waitcnt vmcnt(3)
	v_cvt_pk_f32_fp8_sdwa v[222:223], v48 src0_sel:WORD_1
	v_add_f32_e32 v173, v220, v221
	v_cvt_pk_f32_fp8_e32 v[220:221], v48
	v_pk_mul_f32 v[222:223], v[222:223], v[202:203]
	v_add_f32_dpp v173, v173, v173 quad_perm:[1,0,3,2] row_mask:0xf bank_mask:0xf bound_ctrl:1
	v_pk_fma_f32 v[220:221], v[220:221], v[200:201], v[222:223]
	v_cvt_pk_f32_fp8_e32 v[222:223], v49
	v_add_f32_dpp v173, v173, v173 quad_perm:[2,3,0,1] row_mask:0xf bank_mask:0xf bound_ctrl:1
	v_pk_fma_f32 v[220:221], v[222:223], v[198:199], v[220:221]
	v_cvt_pk_f32_fp8_sdwa v[222:223], v49 src0_sel:WORD_1
	v_add_f32_dpp v173, v173, v173 row_half_mirror row_mask:0xf bank_mask:0xf bound_ctrl:1
	v_cndmask_b32_e64 v147, v147, v173, s[18:19]
	v_pk_fma_f32 v[220:221], v[222:223], v[194:195], v[220:221]
	v_cvt_pk_f32_fp8_e32 v[222:223], v50
	v_pk_fma_f32 v[220:221], v[222:223], v[196:197], v[220:221]
	v_cvt_pk_f32_fp8_sdwa v[222:223], v50 src0_sel:WORD_1
	v_pk_fma_f32 v[220:221], v[222:223], v[150:151], v[220:221]
	v_cvt_pk_f32_fp8_e32 v[222:223], v51
	v_pk_fma_f32 v[220:221], v[222:223], v[148:149], v[220:221]
	v_cvt_pk_f32_fp8_sdwa v[222:223], v51 src0_sel:WORD_1
	v_pk_fma_f32 v[220:221], v[222:223], v[144:145], v[220:221]
	s_waitcnt vmcnt(2)
	v_cvt_pk_f32_fp8_sdwa v[222:223], v52 src0_sel:WORD_1
	v_add_f32_e32 v173, v220, v221
	v_cvt_pk_f32_fp8_e32 v[220:221], v52
	v_pk_mul_f32 v[222:223], v[222:223], v[202:203]
	v_add_f32_dpp v173, v173, v173 quad_perm:[1,0,3,2] row_mask:0xf bank_mask:0xf bound_ctrl:1
	v_pk_fma_f32 v[220:221], v[220:221], v[200:201], v[222:223]
	v_cvt_pk_f32_fp8_e32 v[222:223], v53
	v_add_f32_dpp v173, v173, v173 quad_perm:[2,3,0,1] row_mask:0xf bank_mask:0xf bound_ctrl:1
	v_pk_fma_f32 v[220:221], v[222:223], v[198:199], v[220:221]
	v_cvt_pk_f32_fp8_sdwa v[222:223], v53 src0_sel:WORD_1
	v_add_f32_dpp v173, v173, v173 row_half_mirror row_mask:0xf bank_mask:0xf bound_ctrl:1
	v_cndmask_b32_e64 v147, v147, v173, s[20:21]
	v_pk_fma_f32 v[220:221], v[222:223], v[194:195], v[220:221]
	v_cvt_pk_f32_fp8_e32 v[222:223], v54
	v_pk_fma_f32 v[220:221], v[222:223], v[196:197], v[220:221]
	v_cvt_pk_f32_fp8_sdwa v[222:223], v54 src0_sel:WORD_1
	v_pk_fma_f32 v[220:221], v[222:223], v[150:151], v[220:221]
	v_cvt_pk_f32_fp8_e32 v[222:223], v55
	v_pk_fma_f32 v[220:221], v[222:223], v[148:149], v[220:221]
	v_cvt_pk_f32_fp8_sdwa v[222:223], v55 src0_sel:WORD_1
	v_pk_fma_f32 v[220:221], v[222:223], v[144:145], v[220:221]
	s_waitcnt vmcnt(1)
	v_cvt_pk_f32_fp8_sdwa v[222:223], v56 src0_sel:WORD_1
	v_add_f32_e32 v173, v220, v221
	v_cvt_pk_f32_fp8_e32 v[220:221], v56
	v_pk_mul_f32 v[222:223], v[222:223], v[202:203]
	v_add_f32_dpp v173, v173, v173 quad_perm:[1,0,3,2] row_mask:0xf bank_mask:0xf bound_ctrl:1
	v_pk_fma_f32 v[220:221], v[220:221], v[200:201], v[222:223]
	v_cvt_pk_f32_fp8_e32 v[222:223], v57
	v_add_f32_dpp v173, v173, v173 quad_perm:[2,3,0,1] row_mask:0xf bank_mask:0xf bound_ctrl:1
	v_pk_fma_f32 v[220:221], v[222:223], v[198:199], v[220:221]
	v_cvt_pk_f32_fp8_sdwa v[222:223], v57 src0_sel:WORD_1
	v_add_f32_dpp v173, v173, v173 row_half_mirror row_mask:0xf bank_mask:0xf bound_ctrl:1
	v_cndmask_b32_e64 v147, v147, v173, s[22:23]
	v_pk_fma_f32 v[220:221], v[222:223], v[194:195], v[220:221]
	v_cvt_pk_f32_fp8_e32 v[222:223], v58
	v_pk_fma_f32 v[220:221], v[222:223], v[196:197], v[220:221]
	v_cvt_pk_f32_fp8_sdwa v[222:223], v58 src0_sel:WORD_1
	v_pk_fma_f32 v[220:221], v[222:223], v[150:151], v[220:221]
	v_cvt_pk_f32_fp8_e32 v[222:223], v59
	v_pk_fma_f32 v[220:221], v[222:223], v[148:149], v[220:221]
	v_cvt_pk_f32_fp8_sdwa v[222:223], v59 src0_sel:WORD_1
	v_pk_fma_f32 v[220:221], v[222:223], v[144:145], v[220:221]
	s_waitcnt vmcnt(0)
	v_cvt_pk_f32_fp8_sdwa v[222:223], v60 src0_sel:WORD_1
	v_add_f32_e32 v173, v220, v221
	v_cvt_pk_f32_fp8_e32 v[220:221], v60
	v_pk_mul_f32 v[202:203], v[222:223], v[202:203]
	v_add_f32_dpp v173, v173, v173 quad_perm:[1,0,3,2] row_mask:0xf bank_mask:0xf bound_ctrl:1
	v_pk_fma_f32 v[200:201], v[220:221], v[200:201], v[202:203]
	v_cvt_pk_f32_fp8_e32 v[202:203], v61
	v_add_f32_dpp v173, v173, v173 quad_perm:[2,3,0,1] row_mask:0xf bank_mask:0xf bound_ctrl:1
	v_pk_fma_f32 v[198:199], v[202:203], v[198:199], v[200:201]
	v_cvt_pk_f32_fp8_sdwa v[200:201], v61 src0_sel:WORD_1
	v_add_f32_dpp v173, v173, v173 row_half_mirror row_mask:0xf bank_mask:0xf bound_ctrl:1
	v_cndmask_b32_e64 v147, v147, v173, s[24:25]
	v_pk_fma_f32 v[194:195], v[200:201], v[194:195], v[198:199]
	v_cvt_pk_f32_fp8_e32 v[198:199], v62
	v_pk_fma_f32 v[194:195], v[198:199], v[196:197], v[194:195]
	v_cvt_pk_f32_fp8_sdwa v[196:197], v62 src0_sel:WORD_1
	v_pk_fma_f32 v[150:151], v[196:197], v[150:151], v[194:195]
	v_cvt_pk_f32_fp8_e32 v[194:195], v63
	v_pk_fma_f32 v[148:149], v[194:195], v[148:149], v[150:151]
	v_cvt_pk_f32_fp8_sdwa v[150:151], v63 src0_sel:WORD_1
	v_pk_fma_f32 v[144:145], v[150:151], v[144:145], v[148:149]
	s_nop 0
	v_add_f32_e32 v144, v144, v145
	s_nop 1
	v_add_f32_dpp v144, v144, v144 quad_perm:[1,0,3,2] row_mask:0xf bank_mask:0xf bound_ctrl:1
	s_nop 1
	v_add_f32_dpp v144, v144, v144 quad_perm:[2,3,0,1] row_mask:0xf bank_mask:0xf bound_ctrl:1
	s_nop 1
	v_add_f32_dpp v144, v144, v144 row_half_mirror row_mask:0xf bank_mask:0xf bound_ctrl:1
	v_cndmask_b32_e64 v147, v147, v144, s[26:27]
	v_lshlrev_b64 v[144:145], 9, v[190:191]
	v_lshl_add_u64 v[144:145], v[188:189], 0, v[144:145]
	global_store_dword v[144:145], v146, off
	global_store_dword v[144:145], v147, off offset:256
	s_and_saveexec_b64 s[48:49], s[28:29]
	s_cbranch_execz .LBB0_638
	s_and_saveexec_b64 s[28:29], s[30:31]
	s_cbranch_execz .LBB0_646
	ds_bpermute_b32 v0, v159, v161
	ds_bpermute_b32 v2, v187, v161
	ds_bpermute_b32 v8, v212, v161
	ds_bpermute_b32 v10, v214, v161
	ds_bpermute_b32 v16, v215, v161
	ds_bpermute_b32 v18, v216, v161
	ds_bpermute_b32 v24, v217, v161
	ds_bpermute_b32 v26, v218, v161
	ds_bpermute_b32 v32, v159, v163
	ds_bpermute_b32 v34, v187, v163
	ds_bpermute_b32 v40, v212, v163
	ds_bpermute_b32 v42, v214, v163
	ds_bpermute_b32 v48, v215, v163
	ds_bpermute_b32 v50, v216, v163
	ds_bpermute_b32 v56, v217, v163
	ds_bpermute_b32 v58, v218, v163
	s_waitcnt lgkmcnt(14)
	s_waitcnt lgkmcnt(13)
	s_waitcnt lgkmcnt(12)
	s_waitcnt lgkmcnt(11)
	s_waitcnt lgkmcnt(10)
	s_waitcnt lgkmcnt(9)
	s_waitcnt lgkmcnt(8)
	s_waitcnt lgkmcnt(7)
	s_waitcnt lgkmcnt(6)
	s_waitcnt lgkmcnt(5)
	s_waitcnt lgkmcnt(4)
	s_waitcnt lgkmcnt(3)
	s_waitcnt lgkmcnt(2)
	s_waitcnt lgkmcnt(1)
	s_waitcnt lgkmcnt(0)
	v_lshl_add_u32 v0, v0, 7, v255
	v_lshl_add_u32 v4, v2, 7, v255
	v_lshl_add_u32 v8, v8, 7, v255
	v_lshl_add_u32 v12, v10, 7, v255
	v_lshl_add_u32 v16, v16, 7, v255
	v_lshl_add_u32 v20, v18, 7, v255
	v_lshl_add_u32 v24, v24, 7, v255
	v_lshl_add_u32 v28, v26, 7, v255
	v_lshl_add_u32 v32, v32, 7, v255
	v_lshl_add_u32 v36, v34, 7, v255
	v_lshl_add_u32 v40, v40, 7, v255
	v_lshl_add_u32 v44, v42, 7, v255
	v_lshl_add_u32 v48, v48, 7, v255
	v_lshl_add_u32 v52, v50, 7, v255
	v_lshl_add_u32 v56, v56, 7, v255
	v_lshl_add_u32 v60, v58, 7, v255
	global_load_dwordx4 v[0:3], v0, s[98:99]
	s_nop 0
	global_load_dwordx4 v[4:7], v4, s[98:99]
	s_nop 0
	global_load_dwordx4 v[8:11], v8, s[98:99]
	s_nop 0
	global_load_dwordx4 v[12:15], v12, s[98:99]
	s_nop 0
	global_load_dwordx4 v[16:19], v16, s[98:99]
	s_nop 0
	global_load_dwordx4 v[20:23], v20, s[98:99]
	s_nop 0
	global_load_dwordx4 v[24:27], v24, s[98:99]
	s_nop 0
	global_load_dwordx4 v[28:31], v28, s[98:99]
	s_nop 0
	global_load_dwordx4 v[32:35], v32, s[98:99]
	s_nop 0
	global_load_dwordx4 v[36:39], v36, s[98:99]
	s_nop 0
	global_load_dwordx4 v[40:43], v40, s[98:99]
	s_nop 0
	global_load_dwordx4 v[44:47], v44, s[98:99]
	s_nop 0
	global_load_dwordx4 v[48:51], v48, s[98:99]
	s_nop 0
	global_load_dwordx4 v[52:55], v52, s[98:99]
	s_nop 0
	global_load_dwordx4 v[56:59], v56, s[98:99]
	s_nop 0
	global_load_dwordx4 v[60:63], v60, s[98:99]

.LBB0_654:
	s_or_b64 exec, exec, s[2:3]
	s_add_u32 s48, s94, 0x3a700000
	s_addc_u32 s49, s95, 0
	s_add_u32 s50, s94, 0x3a710000
	s_addc_u32 s51, s95, 0
	s_lshl_b64 s[2:3], s[88:89], 10
	v_mov_b32_e32 v163, 0
	s_mov_b32 s97, 0
	v_lshl_add_u64 v[184:185], s[2:3], 0, v[162:163]
	s_mov_b64 s[2:3], 0x810000
	s_lshl_b64 s[52:53], s[96:97], 10
	v_cmp_gt_u64_e64 s[14:15], s[2:3], v[184:185]
	s_barrier
	s_and_saveexec_b64 s[2:3], s[14:15]
	s_cbranch_execz .LBB0_673
	s_lshl_b64 s[4:5], s[88:89], 12
	s_add_u32 s4, s94, s4
	v_mov_b32_e32 v161, v163
	s_addc_u32 s5, s95, s5
	s_waitcnt vmcnt(5)
	v_lshl_add_u64 v[0:1], s[4:5], 0, v[160:161]
	s_mov_b64 s[4:5], 0xe1c0000
	s_waitcnt vmcnt(1)
	v_lshl_add_u64 v[36:37], v[0:1], 0, s[4:5]
	s_lshl_b64 s[4:5], s[96:97], 12
	s_mov_b64 s[16:17], 0
	s_mov_b32 s20, 0x378e98ab
	s_mov_b32 s21, 0x3b7cd369
	s_mov_b32 s22, 0xbcc618b2
	s_mov_b32 s23, 0x3dda74e4
	s_mov_b32 s24, 0x3f228afd
	s_mov_b32 s25, 0x3e03c728
	s_mov_b32 s26, 0xbfb8aa3b
	s_mov_b32 s27, 0x42ce8ed0
	s_mov_b32 s28, 0xc2b17218
	v_mov_b32_e32 v40, 0x3ba10414
	s_brev_b32 s29, -2
	v_mov_b32_e32 v41, 0xb9c68948
	v_mov_b32_e32 v42, 0x7f800000
	v_mov_b64_e32 v[38:39], v[184:185]
	v_lshrrev_b32_e32 v255, 6, v156
	s_nop 0
	v_readfirstlane_b32 s98, v255
	s_nop 3
	s_mul_i32 s98, s98, 0x2800
	v_subrev_u32_e32 v254, s94, v36
	s_add_u32 m0, s98, 0
	v_add_u32_e32 v255, 0xf9f40000, v254
	global_load_lds_dwordx4 v255, s[94:95]
	s_add_u32 m0, s98, 1024
	v_add_u32_e32 v255, 0xfbf80000, v254
	global_load_lds_dwordx4 v255, s[94:95]
	s_add_u32 m0, s98, 2048
	v_add_u32_e32 v255, 0xfdfc0000, v254
	global_load_lds_dwordx4 v255, s[94:95]
	s_add_u32 m0, s98, 3072
	v_mov_b32_e32 v255, v254
	global_load_lds_dwordx4 v255, s[94:95]
	s_add_u32 m0, s98, 4096
	v_add_u32_e32 v255, 0x2040000, v254
	global_load_lds_dwordx4 v255, s[94:95]
	s_add_u32 m0, s98, 5120
	v_add_u32_e32 v255, 0x4080000, v254
	global_load_lds_dwordx4 v255, s[94:95]
	s_add_u32 m0, s98, 6144
	v_add_u32_e32 v255, 0x60c0000, v254
	global_load_lds_dwordx4 v255, s[94:95]
	s_add_u32 m0, s98, 7168
	v_add_u32_e32 v255, 0x8100000, v254
	global_load_lds_dwordx4 v255, s[94:95]
	s_add_u32 m0, s98, 8192
	v_add_u32_e32 v255, 0xc180000, v254
	global_load_lds_dwordx4 v255, s[94:95]
	s_add_u32 m0, s98, 9216
	v_add_u32_e32 v255, 0xa140000, v254
	global_load_lds_dwordx4 v255, s[94:95]
	s_branch .LBB0_657
.LBB0_656:
	s_or_b64 exec, exec, s[18:19]
	v_bfi_b32 v9, s29, v13, v9
	v_bfi_b32 v10, s29, v14, v10
	v_mul_f32_e32 v1, 0.5, v1
	v_add_f32_e32 v9, 1.0, v9
	v_mul_f32_e32 v2, 0.5, v2
	v_add_f32_e32 v10, 1.0, v10
	v_mul_f32_e32 v1, v1, v9
	v_mul_f32_e32 v2, v2, v10
	v_mul_f32_e32 v1, v5, v1
	v_bfi_b32 v5, s29, v12, v8
	v_bfi_b32 v3, s29, v15, v3
	s_mov_b64 s[18:19], 0xc180000
	v_mul_f32_e32 v2, v6, v2
	v_mul_f32_e32 v6, 0.5, v11
	v_mul_f32_e32 v0, 0.5, v0
	v_add_f32_e32 v5, 1.0, v5
	v_add_f32_e32 v3, 1.0, v3
	v_lshl_add_u64 v[16:17], v[36:37], 0, s[18:19]
	v_mul_f32_e32 v0, v0, v5
	v_mul_f32_e32 v3, v6, v3
	v_lshl_add_u64 v[38:39], v[38:39], 0, s[52:53]
	s_mov_b64 s[18:19], 0x80ffff
	v_mul_f32_e32 v0, v4, v0
	v_mul_f32_e32 v3, v7, v3
	v_cmp_lt_u64_e32 vcc, s[18:19], v[38:39]
	s_waitcnt vmcnt(11)
	v_mul_f32_e32 v2, v45, v2
	v_mul_f32_e32 v1, v44, v1
	v_mul_f32_e32 v0, v43, v0
	s_waitcnt vmcnt(10)
	v_mul_f32_e32 v3, v46, v3
	s_or_b64 s[16:17], vcc, s[16:17]
	v_lshl_add_u64 v[36:37], v[36:37], 0, s[4:5]
	global_store_dwordx4 v[16:17], v[0:3], off
	s_andn2_b64 exec, exec, s[16:17]
	s_cbranch_execz .LBB0_673
.LBB0_657:
	s_waitcnt vmcnt(0)
	v_mbcnt_lo_u32_b32 v255, -1, 0
	v_mbcnt_hi_u32_b32 v255, -1, v255
	v_lshlrev_b32_e32 v255, 4, v255
	v_add_u32_e32 v255, s98, v255
	ds_read_b128 v[0:3], v255 offset:0
	ds_read_b128 v[8:11], v255 offset:1024
	ds_read_b128 v[12:15], v255 offset:2048
	ds_read_b128 v[16:19], v255 offset:3072
	ds_read_b128 v[20:23], v255 offset:4096
	ds_read_b128 v[24:27], v255 offset:5120
	ds_read_b128 v[28:31], v255 offset:6144
	ds_read_b128 v[32:35], v255 offset:7168
	ds_read_b128 v[4:7], v255 offset:8192
	ds_read_b128 v[44:47], v255 offset:9216
	s_waitcnt lgkmcnt(0)
	v_ashrrev_i32_e32 v49, 31, v44
	v_mov_b32_e32 v48, v44
	v_lshlrev_b64 v[50:51], 2, v[48:49]
	v_ashrrev_i32_e32 v53, 31, v45
	v_mov_b32_e32 v52, v45
	v_lshl_add_u64 v[48:49], s[48:49], 0, v[50:51]
	v_lshlrev_b64 v[44:45], 2, v[52:53]
	v_lshl_add_u64 v[52:53], s[48:49], 0, v[44:45]
	global_load_dword v56, v[48:49], off
	s_nop 0
	global_load_dword v49, v[52:53], off
	v_ashrrev_i32_e32 v53, 31, v46
	v_mov_b32_e32 v52, v46
	v_lshlrev_b64 v[52:53], 2, v[52:53]
	v_lshl_add_u64 v[54:55], s[48:49], 0, v[52:53]
	global_load_dword v48, v[54:55], off
	v_ashrrev_i32_e32 v55, 31, v47
	v_mov_b32_e32 v54, v47
	v_lshlrev_b64 v[54:55], 2, v[54:55]
	v_lshl_add_u64 v[46:47], s[48:49], 0, v[54:55]
	v_lshl_add_u64 v[50:51], s[50:51], 0, v[50:51]
	global_load_dword v47, v[46:47], off
	v_lshl_add_u64 v[44:45], s[50:51], 0, v[44:45]
	global_load_dword v43, v[50:51], off
	v_lshl_add_u64 v[50:51], s[50:51], 0, v[52:53]
	global_load_dword v44, v[44:45], off
	v_add_f32_e32 v0, 0, v0
	global_load_dword v45, v[50:51], off
	v_lshl_add_u64 v[50:51], s[50:51], 0, v[54:55]
	global_load_dword v46, v[50:51], off
	v_add_u32_e32 v254, s4, v254
	s_add_u32 m0, s98, 0
	v_add_u32_e32 v255, 0xf9f40000, v254
	global_load_lds_dwordx4 v255, s[94:95]
	s_add_u32 m0, s98, 1024
	v_add_u32_e32 v255, 0xfbf80000, v254
	global_load_lds_dwordx4 v255, s[94:95]
	s_add_u32 m0, s98, 2048
	v_add_u32_e32 v255, 0xfdfc0000, v254
	global_load_lds_dwordx4 v255, s[94:95]
	s_add_u32 m0, s98, 3072
	v_mov_b32_e32 v255, v254
	global_load_lds_dwordx4 v255, s[94:95]
	s_add_u32 m0, s98, 4096
	v_add_u32_e32 v255, 0x2040000, v254
	global_load_lds_dwordx4 v255, s[94:95]
	s_add_u32 m0, s98, 5120
	v_add_u32_e32 v255, 0x4080000, v254
	global_load_lds_dwordx4 v255, s[94:95]
	s_add_u32 m0, s98, 6144
	v_add_u32_e32 v255, 0x60c0000, v254
	global_load_lds_dwordx4 v255, s[94:95]
	s_add_u32 m0, s98, 7168
	v_add_u32_e32 v255, 0x8100000, v254
	global_load_lds_dwordx4 v255, s[94:95]
	s_add_u32 m0, s98, 8192
	v_add_u32_e32 v255, 0xc180000, v254
	global_load_lds_dwordx4 v255, s[94:95]
	s_add_u32 m0, s98, 9216
	v_add_u32_e32 v255, 0xa140000, v254
	global_load_lds_dwordx4 v255, s[94:95]
	v_add_f32_e32 v0, v0, v8
	v_add_f32_e32 v0, v0, v12
	v_add_f32_e32 v0, v0, v16
	v_add_f32_e32 v0, v0, v20
	v_add_f32_e32 v0, v0, v24
	v_add_f32_e32 v0, v0, v28
	v_add_f32_e32 v0, v0, v32
	s_waitcnt vmcnt(17)
	v_mul_f32_e32 v0, v0, v56
	v_mul_f32_e32 v8, 0x3f3504f3, v0
	v_cmp_nlt_f32_e64 s[18:19], |v8|, 1.0
	s_and_saveexec_b64 s[30:31], s[18:19]
	s_xor_b64 s[18:19], exec, s[30:31]
	s_cbranch_execz .LBB0_659
	v_fma_f32 v12, |v8|, s20, v41
	v_fma_f32 v12, |v8|, v12, s21
	v_fma_f32 v12, |v8|, v12, s22
	v_fma_f32 v12, |v8|, v12, s23
	v_fma_f32 v12, |v8|, v12, s24
	v_fma_f32 v12, |v8|, v12, s25
	v_fma_f32 v12, |v8|, v12, |v8|
	v_mul_f32_e32 v16, 0xbfb8aa3b, v12
	v_fma_f32 v20, v12, s26, -v16
	v_rndne_f32_e32 v24, v16
	v_fmac_f32_e32 v20, 0xb2a5705f, v12
	v_sub_f32_e32 v16, v16, v24
	v_add_f32_e32 v16, v16, v20
	v_cvt_i32_f32_e32 v20, v24
	v_exp_f32_e32 v16, v16
	v_cmp_nlt_f32_e32 vcc, s27, v12
	v_ldexp_f32 v16, v16, v20
	s_nop 0
	v_cndmask_b32_e32 v16, 0, v16, vcc
	v_cmp_ngt_f32_e32 vcc, s28, v12
	s_nop 1
	v_cndmask_b32_e32 v12, v42, v16, vcc
	v_sub_f32_e32 v12, 1.0, v12
.LBB0_659:
	s_andn2_saveexec_b64 s[18:19], s[18:19]
	v_mul_f32_e32 v12, v8, v8
	v_fmamk_f32 v16, v12, 0xba1345e1, v40
	v_fmaak_f32 v16, v12, v16, 0xbcdac9b8
	v_fmaak_f32 v16, v12, v16, 0x3de703be
	v_fmaak_f32 v16, v12, v16, 0xbec09330
	v_fmaak_f32 v12, v12, v16, 0x3e0375d0
	v_fma_f32 v12, |v8|, v12, |v8|
	s_or_b64 exec, exec, s[18:19]
	v_add_f32_e32 v1, 0, v1
	v_add_f32_e32 v1, v1, v9
	v_add_f32_e32 v1, v1, v13
	v_add_f32_e32 v1, v1, v17
	v_add_f32_e32 v1, v1, v21
	v_add_f32_e32 v1, v1, v25
	v_add_f32_e32 v1, v1, v29
	v_add_f32_e32 v1, v1, v33
	s_waitcnt vmcnt(16)
	v_mul_f32_e32 v1, v1, v49
	v_mul_f32_e32 v9, 0x3f3504f3, v1
	v_cmp_nlt_f32_e64 s[18:19], |v9|, 1.0
	s_and_saveexec_b64 s[30:31], s[18:19]
	s_xor_b64 s[18:19], exec, s[30:31]
	s_cbranch_execz .LBB0_663
	v_fma_f32 v13, |v9|, s20, v41
	v_fma_f32 v13, |v9|, v13, s21
	v_fma_f32 v13, |v9|, v13, s22
	v_fma_f32 v13, |v9|, v13, s23
	v_fma_f32 v13, |v9|, v13, s24
	v_fma_f32 v13, |v9|, v13, s25
	v_fma_f32 v13, |v9|, v13, |v9|
	v_mul_f32_e32 v16, 0xbfb8aa3b, v13
	v_fma_f32 v17, v13, s26, -v16
	v_rndne_f32_e32 v20, v16
	v_fmac_f32_e32 v17, 0xb2a5705f, v13
	v_sub_f32_e32 v16, v16, v20
	v_add_f32_e32 v16, v16, v17
	v_cvt_i32_f32_e32 v17, v20
	v_exp_f32_e32 v16, v16
	v_cmp_nlt_f32_e32 vcc, s27, v13
	v_ldexp_f32 v16, v16, v17
	s_nop 0
	v_cndmask_b32_e32 v16, 0, v16, vcc
	v_cmp_ngt_f32_e32 vcc, s28, v13
	s_nop 1
	v_cndmask_b32_e32 v13, v42, v16, vcc
	v_sub_f32_e32 v13, 1.0, v13
.LBB0_663:
	s_andn2_saveexec_b64 s[18:19], s[18:19]
	v_mul_f32_e32 v13, v9, v9
	v_fmamk_f32 v16, v13, 0xba1345e1, v40
	v_fmaak_f32 v16, v13, v16, 0xbcdac9b8
	v_fmaak_f32 v16, v13, v16, 0x3de703be
	v_fmaak_f32 v16, v13, v16, 0xbec09330
	v_fmaak_f32 v13, v13, v16, 0x3e0375d0
	v_fma_f32 v13, |v9|, v13, |v9|
	s_or_b64 exec, exec, s[18:19]
	v_add_f32_e32 v2, 0, v2
	v_add_f32_e32 v2, v2, v10
	v_add_f32_e32 v2, v2, v14
	v_add_f32_e32 v2, v2, v18
	v_add_f32_e32 v2, v2, v22
	v_add_f32_e32 v2, v2, v26
	v_add_f32_e32 v2, v2, v30
	v_add_f32_e32 v2, v2, v34
	s_waitcnt vmcnt(15)
	v_mul_f32_e32 v2, v2, v48
	v_mul_f32_e32 v10, 0x3f3504f3, v2
	v_cmp_nlt_f32_e64 s[18:19], |v10|, 1.0
	s_and_saveexec_b64 s[30:31], s[18:19]
	s_xor_b64 s[18:19], exec, s[30:31]
	s_cbranch_execz .LBB0_667
	v_fma_f32 v14, |v10|, s20, v41
	v_fma_f32 v14, |v10|, v14, s21
	v_fma_f32 v14, |v10|, v14, s22
	v_fma_f32 v14, |v10|, v14, s23
	v_fma_f32 v14, |v10|, v14, s24
	v_fma_f32 v14, |v10|, v14, s25
	v_fma_f32 v14, |v10|, v14, |v10|
	v_mul_f32_e32 v16, 0xbfb8aa3b, v14
	v_fma_f32 v17, v14, s26, -v16
	v_rndne_f32_e32 v18, v16
	v_fmac_f32_e32 v17, 0xb2a5705f, v14
	v_sub_f32_e32 v16, v16, v18
	v_add_f32_e32 v16, v16, v17
	v_cvt_i32_f32_e32 v17, v18
	v_exp_f32_e32 v16, v16
	v_cmp_nlt_f32_e32 vcc, s27, v14
	v_ldexp_f32 v16, v16, v17
	s_nop 0
	v_cndmask_b32_e32 v16, 0, v16, vcc
	v_cmp_ngt_f32_e32 vcc, s28, v14
	s_nop 1
	v_cndmask_b32_e32 v14, v42, v16, vcc
	v_sub_f32_e32 v14, 1.0, v14
.LBB0_667:
	s_andn2_saveexec_b64 s[18:19], s[18:19]
	v_mul_f32_e32 v14, v10, v10
	v_fmamk_f32 v16, v14, 0xba1345e1, v40
	v_fmaak_f32 v16, v14, v16, 0xbcdac9b8
	v_fmaak_f32 v16, v14, v16, 0x3de703be
	v_fmaak_f32 v16, v14, v16, 0xbec09330
	v_fmaak_f32 v14, v14, v16, 0x3e0375d0
	v_fma_f32 v14, |v10|, v14, |v10|
	s_or_b64 exec, exec, s[18:19]
	v_add_f32_e32 v3, 0, v3
	v_add_f32_e32 v3, v3, v11
	v_add_f32_e32 v3, v3, v15
	v_add_f32_e32 v3, v3, v19
	v_add_f32_e32 v3, v3, v23
	v_add_f32_e32 v3, v3, v27
	v_add_f32_e32 v3, v3, v31
	v_add_f32_e32 v3, v3, v35
	s_waitcnt vmcnt(14)
	v_mul_f32_e32 v11, v3, v47
	v_mul_f32_e32 v3, 0x3f3504f3, v11
	v_cmp_nlt_f32_e64 s[18:19], |v3|, 1.0
	s_and_saveexec_b64 s[30:31], s[18:19]
	s_xor_b64 s[18:19], exec, s[30:31]
	s_cbranch_execz .LBB0_671
	v_fma_f32 v15, |v3|, s20, v41
	v_fma_f32 v15, |v3|, v15, s21
	v_fma_f32 v15, |v3|, v15, s22
	v_fma_f32 v15, |v3|, v15, s23
	v_fma_f32 v15, |v3|, v15, s24
	v_fma_f32 v15, |v3|, v15, s25
	v_fma_f32 v15, |v3|, v15, |v3|
	v_mul_f32_e32 v16, 0xbfb8aa3b, v15
	v_fma_f32 v17, v15, s26, -v16
	v_rndne_f32_e32 v18, v16
	v_fmac_f32_e32 v17, 0xb2a5705f, v15
	v_sub_f32_e32 v16, v16, v18
	v_add_f32_e32 v16, v16, v17
	v_cvt_i32_f32_e32 v17, v18
	v_exp_f32_e32 v16, v16
	v_cmp_nlt_f32_e32 vcc, s27, v15
	v_ldexp_f32 v16, v16, v17
	s_nop 0
	v_cndmask_b32_e32 v16, 0, v16, vcc
	v_cmp_ngt_f32_e32 vcc, s28, v15
	s_nop 1
	v_cndmask_b32_e32 v15, v42, v16, vcc
	v_sub_f32_e32 v15, 1.0, v15

.LBB0_679:
	s_or_b64 exec, exec, s[2:3]
	s_add_u32 s2, s94, s35
	s_addc_u32 s3, s95, 0
	s_waitcnt vmcnt(5)
	v_lshl_add_u64 v[0:1], s[2:3], 0, v[170:171]
	s_mov_b64 s[2:3], 0x39700000
	v_lshl_add_u64 v[180:181], v[0:1], 0, s[2:3]
	s_add_u32 s2, s94, 0x20400000
	v_readlane_b32 s4, v252, 27
	s_addc_u32 s3, s95, 0
	s_mul_i32 s4, s4, 0x40800
	s_add_u32 s30, s2, s4
	s_addc_u32 s31, s3, 0
	v_lshlrev_b32_e32 v171, 1, v210
	s_barrier
	s_and_saveexec_b64 s[4:5], s[12:13]
	s_cbranch_execz .LBB0_698
	v_mov_b32_e32 v129, 0
	v_lshlrev_b64 v[0:1], 9, v[174:175]
	v_lshl_add_u64 v[2:3], s[38:39], 0, v[0:1]
	v_mov_b32_e32 v173, v129
	s_waitcnt vmcnt(1)
	v_or_b32_e32 v4, 0x100, v0
	s_waitcnt vmcnt(0)
	v_mov_b32_e32 v5, v1
	v_lshl_add_u64 v[0:1], s[36:37], 0, v[0:1]
	v_lshl_add_u64 v[130:131], s[38:39], 0, v[172:173]
	v_lshl_add_u64 v[0:1], v[0:1], 0, v[172:173]
	v_lshl_add_u64 v[132:133], s[36:37], 0, v[172:173]
	v_lshl_add_u64 v[2:3], v[2:3], 0, v[172:173]
	v_lshl_add_u64 v[6:7], v[130:131], 0, v[4:5]
	v_lshl_add_u64 v[4:5], v[132:133], 0, v[4:5]
	global_load_dword v150, v[0:1], off
	global_load_dword v151, v[4:5], off
	global_load_dword v148, v[2:3], off
	global_load_dword v149, v[6:7], off
	v_readlane_b32 s16, v252, 27
	s_lshl_b32 s16, s16, 7
	v_lshlrev_b64 v[0:1], 12, v[174:175]
	v_or3_b32 v2, v171, s16, v170
	v_lshl_add_u64 v[0:1], s[92:93], 0, v[0:1]
	v_lshlrev_b32_e32 v128, 2, v2
	v_mbcnt_hi_u32_b32 v64, -1, v155
	v_lshl_add_u64 v[0:1], v[0:1], 0, v[128:129]
	s_mov_b32 s35, 0xffff0000
	v_and_or_b32 v4, v64, 64, v210
	global_load_dwordx2 v[144:145], v[0:1], off
	v_lshlrev_b32_e32 v159, 2, v4
	v_mov_b32_e32 v3, v129
	v_mov_b32_e32 v5, v129
	v_mov_b32_e32 v7, v129
	v_mov_b32_e32 v9, v129
	v_mov_b32_e32 v11, v129
	v_mov_b32_e32 v13, v129
	v_mov_b32_e32 v15, v129
	v_mov_b32_e32 v17, v129
	v_mov_b32_e32 v19, v129
	v_mov_b32_e32 v21, v129
	v_mov_b32_e32 v41, v129
	v_mov_b32_e32 v43, v129
	v_mov_b32_e32 v49, v129
	v_mov_b32_e32 v51, v129
	v_mov_b32_e32 v57, v129
	v_mov_b32_e32 v59, v129
	s_mov_b32 s54, 0x10200
	v_cmp_gt_i32_e32 vcc, s54, v176
	s_waitcnt vmcnt(4)
	v_cvt_pk_bf16_f32 v0, v129, v150
	s_waitcnt vmcnt(3)
	v_cvt_pk_bf16_f32 v1, v129, v151
	v_and_b32_e32 v255, 7, v156
	v_lshlrev_b32_e32 v255, 4, v255
	v_readfirstlane_b32 s98, v180
	v_readfirstlane_b32 s99, v181
	s_mov_b32 s100, 0x7fff80
	s_waitcnt vmcnt(2)
	v_and_or_b32 v0, v0, s35, v148
	s_waitcnt vmcnt(1)
	v_and_or_b32 v56, v1, s35, v149
	ds_bpermute_b32 v161, v159, v0
	ds_bpermute_b32 v163, v159, v0 offset:32
	ds_bpermute_b32 v183, v159, v0 offset:64
	ds_bpermute_b32 v187, v159, v0 offset:96
	ds_bpermute_b32 v188, v159, v0 offset:128
	ds_bpermute_b32 v189, v159, v0 offset:160
	ds_bpermute_b32 v190, v159, v0 offset:192
	ds_bpermute_b32 v191, v159, v0 offset:224
	ds_bpermute_b32 v192, v159, v56
	ds_bpermute_b32 v193, v159, v56 offset:32
	s_waitcnt lgkmcnt(9)
	v_lshlrev_b32_e32 v0, 7, v161
	s_waitcnt lgkmcnt(8)
	v_lshlrev_b32_e32 v1, 7, v163
	s_waitcnt lgkmcnt(7)
	v_lshlrev_b32_e32 v6, 7, v183
	s_waitcnt lgkmcnt(6)
	v_lshlrev_b32_e32 v8, 7, v187
	s_waitcnt lgkmcnt(5)
	v_lshlrev_b32_e32 v10, 7, v188
	s_waitcnt lgkmcnt(4)
	v_lshlrev_b32_e32 v12, 7, v189
	s_waitcnt lgkmcnt(3)
	v_lshlrev_b32_e32 v14, 7, v190
	s_waitcnt lgkmcnt(2)
	v_lshlrev_b32_e32 v16, 7, v191
	s_waitcnt lgkmcnt(1)
	v_lshlrev_b32_e32 v18, 7, v192
	s_waitcnt lgkmcnt(0)
	v_lshlrev_b32_e32 v20, 7, v193
	v_and_or_b32 v0, v0, s100, v255
	v_and_or_b32 v4, v1, s100, v255
	v_and_or_b32 v22, v6, s100, v255
	v_and_or_b32 v24, v8, s100, v255
	v_and_or_b32 v26, v10, s100, v255
	v_and_or_b32 v28, v12, s100, v255
	v_and_or_b32 v30, v14, s100, v255
	v_and_or_b32 v32, v16, s100, v255
	v_and_or_b32 v34, v18, s100, v255
	v_and_or_b32 v36, v20, s100, v255
	ds_bpermute_b32 v194, v159, v56 offset:64
	ds_bpermute_b32 v196, v159, v56 offset:96
	global_load_dwordx4 v[0:3], v0, s[98:99]
	s_nop 0
	global_load_dwordx4 v[4:7], v4, s[98:99]
	s_nop 0
	global_load_dwordx4 v[8:11], v22, s[98:99]
	global_load_dwordx4 v[12:15], v24, s[98:99]
	global_load_dwordx4 v[16:19], v26, s[98:99]
	s_nop 0
	global_load_dwordx4 v[20:23], v28, s[98:99]
	global_load_dwordx4 v[24:27], v30, s[98:99]
	s_nop 0
	global_load_dwordx4 v[28:31], v32, s[98:99]
	s_nop 0
	global_load_dwordx4 v[32:35], v34, s[98:99]
	s_nop 0
	global_load_dwordx4 v[36:39], v36, s[98:99]
	ds_bpermute_b32 v215, v159, v56 offset:128
	ds_bpermute_b32 v217, v159, v56 offset:160
	ds_bpermute_b32 v218, v159, v56 offset:192
	ds_bpermute_b32 v219, v159, v56 offset:224
	s_waitcnt lgkmcnt(5)
	v_lshlrev_b32_e32 v40, 7, v194
	s_waitcnt lgkmcnt(4)
	v_lshlrev_b32_e32 v42, 7, v196
	s_waitcnt lgkmcnt(3)
	v_lshlrev_b32_e32 v48, 7, v215
	s_waitcnt lgkmcnt(2)
	v_lshlrev_b32_e32 v50, 7, v217
	s_waitcnt lgkmcnt(1)
	v_lshlrev_b32_e32 v56, 7, v218
	s_waitcnt lgkmcnt(0)
	v_lshlrev_b32_e32 v58, 7, v219
	v_and_or_b32 v40, v40, s100, v255
	v_and_or_b32 v44, v42, s100, v255
	v_and_or_b32 v48, v48, s100, v255
	v_and_or_b32 v52, v50, s100, v255
	v_and_or_b32 v56, v56, s100, v255
	v_and_or_b32 v60, v58, s100, v255
	global_load_dwordx4 v[40:43], v40, s[98:99]
	s_nop 0
	global_load_dwordx4 v[44:47], v44, s[98:99]
	s_nop 0
	global_load_dwordx4 v[48:51], v48, s[98:99]
	s_nop 0
	global_load_dwordx4 v[52:55], v52, s[98:99]
	s_nop 0
	global_load_dwordx4 v[56:59], v56, s[98:99]
	s_nop 0
	global_load_dwordx4 v[60:63], v60, s[98:99]
	s_and_saveexec_b64 s[16:17], vcc
	s_cbranch_execz .LBB0_682
	v_ashrrev_i32_e32 v177, 31, v176
	v_lshlrev_b64 v[66:67], 9, v[176:177]
	v_lshl_add_u64 v[68:69], s[38:39], 0, v[66:67]
	v_lshl_add_u64 v[68:69], v[68:69], 0, v[172:173]
	global_load_dword v195, v[68:69], off
	v_or_b32_e32 v68, 0x100, v66
	v_mov_b32_e32 v69, v67
	v_lshl_add_u64 v[66:67], s[36:37], 0, v[66:67]
	v_lshl_add_u64 v[70:71], v[130:131], 0, v[68:69]
	v_lshl_add_u64 v[66:67], v[66:67], 0, v[172:173]
	global_load_dword v197, v[70:71], off
	global_load_dword v198, v[66:67], off
	v_lshl_add_u64 v[66:67], v[132:133], 0, v[68:69]
	global_load_dword v199, v[66:67], off
	v_lshlrev_b64 v[66:67], 12, v[176:177]
	v_lshl_add_u64 v[66:67], s[92:93], 0, v[66:67]
	v_lshl_add_u64 v[66:67], v[66:67], 0, v[128:129]
	global_load_dwordx2 v[136:137], v[66:67], off

.LBB0_685:
	v_add_u32_e32 v138, s68, v142
	v_cmp_gt_i32_e64 s[20:21], s54, v138
	s_and_saveexec_b64 s[22:23], s[20:21]
	s_cbranch_execz .LBB0_687
	s_waitcnt vmcnt(2)
	v_cvt_pk_bf16_f32 v64, v129, v198
	s_nop 0
	v_and_or_b32 v84, v64, s35, v195
	ds_bpermute_b32 v220, v159, v84
	ds_bpermute_b32 v221, v173, v84
	ds_bpermute_b32 v222, v177, v84
	ds_bpermute_b32 v223, v200, v84
	s_waitcnt vmcnt(1)
	v_cvt_pk_bf16_f32 v64, v129, v199
	ds_bpermute_b32 v224, v201, v84
	v_and_or_b32 v116, v64, s35, v197
	s_waitcnt lgkmcnt(4)
	v_lshlrev_b32_e32 v64, 7, v220
	ds_bpermute_b32 v225, v202, v84
	s_waitcnt lgkmcnt(4)
	v_lshlrev_b32_e32 v66, 7, v221
	ds_bpermute_b32 v226, v203, v84
	v_and_or_b32 v64, v64, s100, v255
	s_waitcnt lgkmcnt(4)
	v_lshlrev_b32_e32 v72, 7, v222
	ds_bpermute_b32 v227, v212, v84
	v_and_or_b32 v66, v66, s100, v255
	s_waitcnt lgkmcnt(4)
	v_lshlrev_b32_e32 v74, 7, v223
	ds_bpermute_b32 v228, v159, v116
	v_and_or_b32 v72, v72, s100, v255
	s_waitcnt lgkmcnt(4)
	v_lshlrev_b32_e32 v80, 7, v224
	ds_bpermute_b32 v229, v173, v116
	v_and_or_b32 v74, v74, s100, v255
	s_waitcnt lgkmcnt(4)
	v_lshlrev_b32_e32 v82, 7, v225
	ds_bpermute_b32 v230, v177, v116
	v_and_or_b32 v80, v80, s100, v255
	s_waitcnt lgkmcnt(4)
	v_lshlrev_b32_e32 v88, 7, v226
	ds_bpermute_b32 v231, v200, v116
	v_and_or_b32 v82, v82, s100, v255
	s_waitcnt lgkmcnt(4)
	v_lshlrev_b32_e32 v90, 7, v227
	ds_bpermute_b32 v232, v201, v116
	v_and_or_b32 v88, v88, s100, v255
	s_waitcnt lgkmcnt(4)
	v_lshlrev_b32_e32 v96, 7, v228
	ds_bpermute_b32 v233, v202, v116
	v_and_or_b32 v90, v90, s100, v255
	s_waitcnt lgkmcnt(4)
	v_lshlrev_b32_e32 v98, 7, v229
	ds_bpermute_b32 v234, v203, v116
	v_and_or_b32 v96, v96, s100, v255
	s_waitcnt lgkmcnt(4)
	v_lshlrev_b32_e32 v104, 7, v230
	ds_bpermute_b32 v235, v212, v116
	v_and_or_b32 v98, v98, s100, v255
	s_waitcnt lgkmcnt(4)
	v_lshlrev_b32_e32 v106, 7, v231
	v_and_or_b32 v104, v104, s100, v255
	s_waitcnt lgkmcnt(3)
	v_lshlrev_b32_e32 v112, 7, v232
	v_and_or_b32 v106, v106, s100, v255
	s_waitcnt lgkmcnt(2)
	v_lshlrev_b32_e32 v114, 7, v233
	v_and_or_b32 v112, v112, s100, v255
	s_waitcnt lgkmcnt(1)
	v_lshlrev_b32_e32 v120, 7, v234
	v_and_or_b32 v114, v114, s100, v255
	s_waitcnt lgkmcnt(0)
	v_lshlrev_b32_e32 v122, 7, v235
	v_and_or_b32 v120, v120, s100, v255
	v_and_or_b32 v122, v122, s100, v255
	global_load_dwordx4 v[68:71], v64, s[98:99]
	s_nop 0
	global_load_dwordx4 v[64:67], v66, s[98:99]
	s_nop 0
	global_load_dwordx4 v[76:79], v72, s[98:99]
	s_nop 0
	global_load_dwordx4 v[72:75], v74, s[98:99]
	s_nop 0
	global_load_dwordx4 v[84:87], v80, s[98:99]
	s_nop 0
	global_load_dwordx4 v[80:83], v82, s[98:99]
	s_nop 0
	global_load_dwordx4 v[92:95], v88, s[98:99]
	s_nop 0
	global_load_dwordx4 v[88:91], v90, s[98:99]
	s_nop 0
	global_load_dwordx4 v[100:103], v96, s[98:99]
	s_nop 0
	global_load_dwordx4 v[96:99], v98, s[98:99]
	s_nop 0
	global_load_dwordx4 v[108:111], v104, s[98:99]
	s_nop 0
	global_load_dwordx4 v[104:107], v106, s[98:99]
	s_nop 0
	global_load_dwordx4 v[116:119], v112, s[98:99]
	s_nop 0
	global_load_dwordx4 v[112:115], v114, s[98:99]
	s_nop 0
	global_load_dwordx4 v[124:127], v120, s[98:99]
	s_nop 0
	global_load_dwordx4 v[120:123], v122, s[98:99]

.LBB0_691:
	s_or_b64 exec, exec, s[26:27]
	s_mov_b64 s[28:29], -1
	s_and_saveexec_b64 s[26:27], s[20:21]
	s_cbranch_execz .LBB0_684
	s_and_saveexec_b64 s[20:21], s[22:23]
	s_cbranch_execz .LBB0_694
	v_cvt_pk_bf16_f32 v0, v129, v150
	s_nop 0
	v_and_or_b32 v18, v0, s35, v148
	ds_bpermute_b32 v161, v159, v18
	ds_bpermute_b32 v163, v173, v18
	ds_bpermute_b32 v183, v177, v18
	ds_bpermute_b32 v187, v200, v18
	v_cvt_pk_bf16_f32 v0, v129, v151
	ds_bpermute_b32 v188, v201, v18
	v_and_or_b32 v50, v0, s35, v149
	s_waitcnt lgkmcnt(4)
	v_lshlrev_b32_e32 v0, 7, v161
	ds_bpermute_b32 v189, v202, v18
	s_waitcnt lgkmcnt(4)
	v_lshlrev_b32_e32 v2, 7, v163
	ds_bpermute_b32 v190, v203, v18
	v_and_or_b32 v0, v0, s100, v255
	s_waitcnt lgkmcnt(4)
	v_lshlrev_b32_e32 v8, 7, v183
	ds_bpermute_b32 v191, v212, v18
	v_and_or_b32 v4, v2, s100, v255
	s_waitcnt lgkmcnt(4)
	v_lshlrev_b32_e32 v10, 7, v187
	ds_bpermute_b32 v192, v159, v50
	v_and_or_b32 v8, v8, s100, v255
	s_waitcnt lgkmcnt(4)
	v_lshlrev_b32_e32 v16, 7, v188
	ds_bpermute_b32 v193, v173, v50
	v_and_or_b32 v12, v10, s100, v255
	s_waitcnt lgkmcnt(4)
	v_lshlrev_b32_e32 v19, 7, v189
	ds_bpermute_b32 v194, v177, v50
	v_and_or_b32 v16, v16, s100, v255
	s_waitcnt lgkmcnt(4)
	v_lshlrev_b32_e32 v24, 7, v190
	ds_bpermute_b32 v196, v200, v50
	v_and_or_b32 v20, v19, s100, v255
	s_waitcnt lgkmcnt(4)
	v_lshlrev_b32_e32 v26, 7, v191
	ds_bpermute_b32 v215, v201, v50
	v_and_or_b32 v24, v24, s100, v255
	s_waitcnt lgkmcnt(4)
	v_lshlrev_b32_e32 v32, 7, v192
	ds_bpermute_b32 v217, v202, v50
	v_and_or_b32 v28, v26, s100, v255
	s_waitcnt lgkmcnt(4)
	v_lshlrev_b32_e32 v34, 7, v193
	ds_bpermute_b32 v218, v203, v50
	v_and_or_b32 v32, v32, s100, v255
	s_waitcnt lgkmcnt(4)
	v_lshlrev_b32_e32 v40, 7, v194
	ds_bpermute_b32 v219, v212, v50
	v_and_or_b32 v36, v34, s100, v255
	s_waitcnt lgkmcnt(4)
	v_lshlrev_b32_e32 v42, 7, v196
	v_and_or_b32 v40, v40, s100, v255
	s_waitcnt lgkmcnt(3)
	v_lshlrev_b32_e32 v48, 7, v215
	v_and_or_b32 v44, v42, s100, v255
	s_waitcnt lgkmcnt(2)
	v_lshlrev_b32_e32 v51, 7, v217
	v_and_or_b32 v48, v48, s100, v255
	s_waitcnt lgkmcnt(1)
	v_lshlrev_b32_e32 v56, 7, v218
	v_and_or_b32 v52, v51, s100, v255
	s_waitcnt lgkmcnt(0)
	v_lshlrev_b32_e32 v58, 7, v219
	v_and_or_b32 v56, v56, s100, v255
	v_and_or_b32 v60, v58, s100, v255
	global_load_dwordx4 v[0:3], v0, s[98:99]
	s_nop 0
	global_load_dwordx4 v[4:7], v4, s[98:99]
	s_nop 0
	global_load_dwordx4 v[8:11], v8, s[98:99]
	s_nop 0
	global_load_dwordx4 v[12:15], v12, s[98:99]
	s_nop 0
	global_load_dwordx4 v[16:19], v16, s[98:99]
	s_nop 0
	global_load_dwordx4 v[20:23], v20, s[98:99]
	s_nop 0
	global_load_dwordx4 v[24:27], v24, s[98:99]
	s_nop 0
	global_load_dwordx4 v[28:31], v28, s[98:99]
	s_nop 0
	global_load_dwordx4 v[32:35], v32, s[98:99]
	s_nop 0
	global_load_dwordx4 v[36:39], v36, s[98:99]
	s_nop 0
	global_load_dwordx4 v[40:43], v40, s[98:99]
	s_nop 0
	global_load_dwordx4 v[44:47], v44, s[98:99]
	s_nop 0
	global_load_dwordx4 v[48:51], v48, s[98:99]
	s_nop 0
	global_load_dwordx4 v[52:55], v52, s[98:99]
	s_nop 0
	global_load_dwordx4 v[56:59], v56, s[98:99]
	s_nop 0
	global_load_dwordx4 v[60:63], v60, s[98:99]

.LBB0_1095:
	s_or_b64 exec, exec, s[0:1]
	s_barrier
	s_and_saveexec_b64 s[0:1], s[12:13]
	s_cbranch_execz .LBB0_1110
	v_mov_b32_e32 v183, 0
	v_lshlrev_b64 v[0:1], 9, v[174:175]
	v_lshl_add_u64 v[0:1], s[38:39], 0, v[0:1]
	v_mov_b32_e32 v173, v183
	v_lshl_add_u64 v[0:1], v[0:1], 0, v[172:173]
	global_load_dword v159, v[0:1], off
	global_load_dword v161, v[0:1], off offset:256
	v_lshlrev_b64 v[0:1], 11, v[174:175]
	v_readlane_b32 s4, v252, 27
	s_mov_b32 s3, 0
	s_lshl_b32 s2, s4, 8
	v_mbcnt_hi_u32_b32 v2, -1, v155
	v_lshl_add_u64 v[0:1], s[94:95], 0, v[0:1]
	v_and_or_b32 v2, v2, 64, v210
	v_lshl_add_u64 v[0:1], v[0:1], 0, s[2:3]
	v_lshlrev_b32_e32 v157, 2, v2
	v_lshl_add_u64 v[0:1], v[0:1], 0, v[182:183]
	global_load_dwordx4 v[144:147], v[0:1], off offset:16
	global_load_dwordx4 v[148:151], v[0:1], off
	s_mov_b32 s35, 0x10200
	s_lshl_b32 s6, s4, 7
	v_cmp_gt_i32_e32 vcc, s35, v176
	v_and_b32_e32 v255, 7, v156
	v_lshlrev_b32_e32 v255, 4, v255
	v_readfirstlane_b32 s98, v178
	v_readfirstlane_b32 s99, v179
	s_waitcnt vmcnt(3)
	ds_bpermute_b32 v0, v157, v159
	ds_bpermute_b32 v2, v157, v159 offset:32
	ds_bpermute_b32 v4, v157, v159 offset:64
	ds_bpermute_b32 v6, v157, v159 offset:96
	ds_bpermute_b32 v8, v157, v159 offset:128
	ds_bpermute_b32 v10, v157, v159 offset:160
	ds_bpermute_b32 v12, v157, v159 offset:192
	ds_bpermute_b32 v14, v157, v159 offset:224
	s_waitcnt vmcnt(2)
	ds_bpermute_b32 v16, v157, v161
	ds_bpermute_b32 v18, v157, v161 offset:32
	ds_bpermute_b32 v20, v157, v161 offset:64
	ds_bpermute_b32 v22, v157, v161 offset:96
	ds_bpermute_b32 v24, v157, v161 offset:128
	ds_bpermute_b32 v26, v157, v161 offset:160
	ds_bpermute_b32 v28, v157, v161 offset:192
	s_waitcnt lgkmcnt(14)
	s_waitcnt lgkmcnt(13)
	s_waitcnt lgkmcnt(12)
	s_waitcnt lgkmcnt(11)
	s_waitcnt lgkmcnt(10)
	s_waitcnt lgkmcnt(9)
	s_waitcnt lgkmcnt(8)
	s_waitcnt lgkmcnt(7)
	s_waitcnt lgkmcnt(6)
	s_waitcnt lgkmcnt(5)
	s_waitcnt lgkmcnt(4)
	s_waitcnt lgkmcnt(3)
	s_waitcnt lgkmcnt(2)
	s_waitcnt lgkmcnt(1)
	s_waitcnt lgkmcnt(0)
	v_lshl_add_u32 v60, v0, 7, v255
	v_lshl_add_u32 v58, v28, 7, v255
	v_lshl_add_u32 v62, v2, 7, v255
	v_lshl_add_u32 v64, v4, 7, v255
	v_lshl_add_u32 v66, v6, 7, v255
	v_lshl_add_u32 v68, v8, 7, v255
	v_lshl_add_u32 v70, v10, 7, v255
	v_lshl_add_u32 v72, v12, 7, v255
	v_lshl_add_u32 v74, v14, 7, v255
	v_lshl_add_u32 v76, v16, 7, v255
	v_lshl_add_u32 v78, v18, 7, v255
	v_lshl_add_u32 v80, v20, 7, v255
	v_lshl_add_u32 v82, v22, 7, v255
	v_lshl_add_u32 v84, v24, 7, v255
	v_lshl_add_u32 v86, v26, 7, v255
	global_load_dwordx4 v[0:3], v60, s[98:99]
	global_load_dwordx4 v[4:7], v62, s[98:99]
	global_load_dwordx4 v[8:11], v64, s[98:99]
	global_load_dwordx4 v[12:15], v66, s[98:99]
	global_load_dwordx4 v[16:19], v68, s[98:99]
	global_load_dwordx4 v[20:23], v70, s[98:99]
	global_load_dwordx4 v[24:27], v72, s[98:99]
	global_load_dwordx4 v[28:31], v74, s[98:99]
	global_load_dwordx4 v[32:35], v76, s[98:99]
	global_load_dwordx4 v[36:39], v78, s[98:99]
	global_load_dwordx4 v[40:43], v80, s[98:99]
	global_load_dwordx4 v[44:47], v82, s[98:99]
	global_load_dwordx4 v[48:51], v84, s[98:99]
	global_load_dwordx4 v[52:55], v86, s[98:99]
	ds_bpermute_b32 v56, v157, v161 offset:224
	s_waitcnt lgkmcnt(0)
	v_lshl_add_u32 v56, v56, 7, v255
	global_load_dwordx4 v[64:67], v58, s[98:99]
	global_load_dwordx4 v[68:71], v56, s[98:99]
	s_and_saveexec_b64 s[4:5], vcc
	s_cbranch_execz .LBB0_1098
	v_ashrrev_i32_e32 v177, 31, v176
	v_lshlrev_b64 v[56:57], 11, v[176:177]
	v_lshl_add_u64 v[56:57], s[94:95], 0, v[56:57]
	s_lshl_b32 s2, s6, 1
	v_lshl_add_u64 v[56:57], v[56:57], 0, s[2:3]
	v_lshl_add_u64 v[56:57], v[56:57], 0, v[182:183]
	global_load_dwordx4 v[136:139], v[56:57], off offset:16
	global_load_dwordx4 v[140:143], v[56:57], off
	v_lshlrev_b64 v[56:57], 9, v[176:177]
	v_lshl_add_u64 v[56:57], s[38:39], 0, v[56:57]
	v_lshl_add_u64 v[56:57], v[56:57], 0, v[172:173]
	global_load_dword v177, v[56:57], off
	global_load_dword v195, v[56:57], off offset:256

.LBB0_1101:
	v_add_u32_e32 v182, s68, v168
	v_cmp_gt_i32_e64 s[26:27], s35, v182
	s_and_saveexec_b64 s[4:5], s[26:27]
	s_cbranch_execz .LBB0_1103
	s_waitcnt vmcnt(1)
	ds_bpermute_b32 v56, v157, v177
	ds_bpermute_b32 v58, v194, v177
	ds_bpermute_b32 v72, v196, v177
	ds_bpermute_b32 v74, v197, v177
	ds_bpermute_b32 v80, v198, v177
	ds_bpermute_b32 v82, v199, v177
	ds_bpermute_b32 v88, v200, v177
	ds_bpermute_b32 v90, v201, v177
	s_waitcnt vmcnt(0)
	ds_bpermute_b32 v96, v157, v195
	ds_bpermute_b32 v98, v194, v195
	ds_bpermute_b32 v104, v196, v195
	ds_bpermute_b32 v106, v197, v195
	ds_bpermute_b32 v112, v198, v195
	ds_bpermute_b32 v114, v199, v195
	ds_bpermute_b32 v120, v200, v195
	ds_bpermute_b32 v122, v201, v195
	s_waitcnt lgkmcnt(14)
	s_waitcnt lgkmcnt(13)
	s_waitcnt lgkmcnt(12)
	s_waitcnt lgkmcnt(11)
	s_waitcnt lgkmcnt(10)
	s_waitcnt lgkmcnt(9)
	s_waitcnt lgkmcnt(8)
	s_waitcnt lgkmcnt(7)
	s_waitcnt lgkmcnt(6)
	s_waitcnt lgkmcnt(5)
	s_waitcnt lgkmcnt(4)
	s_waitcnt lgkmcnt(3)
	s_waitcnt lgkmcnt(2)
	s_waitcnt lgkmcnt(1)
	s_waitcnt lgkmcnt(0)
	v_lshl_add_u32 v56, v56, 7, v255
	v_lshl_add_u32 v58, v58, 7, v255
	v_lshl_add_u32 v72, v72, 7, v255
	v_lshl_add_u32 v74, v74, 7, v255
	v_lshl_add_u32 v80, v80, 7, v255
	v_lshl_add_u32 v82, v82, 7, v255
	v_lshl_add_u32 v88, v88, 7, v255
	v_lshl_add_u32 v90, v90, 7, v255
	v_lshl_add_u32 v96, v96, 7, v255
	v_lshl_add_u32 v98, v98, 7, v255
	v_lshl_add_u32 v104, v104, 7, v255
	v_lshl_add_u32 v106, v106, 7, v255
	v_lshl_add_u32 v112, v112, 7, v255
	v_lshl_add_u32 v114, v114, 7, v255
	v_lshl_add_u32 v120, v120, 7, v255
	v_lshl_add_u32 v122, v122, 7, v255
	global_load_dwordx4 v[60:63], v56, s[98:99]
	s_nop 0
	global_load_dwordx4 v[56:59], v58, s[98:99]
	s_nop 0
	global_load_dwordx4 v[76:79], v72, s[98:99]
	s_nop 0
	global_load_dwordx4 v[72:75], v74, s[98:99]
	s_nop 0
	global_load_dwordx4 v[84:87], v80, s[98:99]
	s_nop 0
	global_load_dwordx4 v[80:83], v82, s[98:99]
	s_nop 0
	global_load_dwordx4 v[92:95], v88, s[98:99]
	s_nop 0
	global_load_dwordx4 v[88:91], v90, s[98:99]
	s_nop 0
	global_load_dwordx4 v[100:103], v96, s[98:99]
	s_nop 0
	global_load_dwordx4 v[96:99], v98, s[98:99]
	s_nop 0
	global_load_dwordx4 v[108:111], v104, s[98:99]
	s_nop 0
	global_load_dwordx4 v[104:107], v106, s[98:99]
	s_nop 0
	global_load_dwordx4 v[116:119], v112, s[98:99]
	s_nop 0
	global_load_dwordx4 v[112:115], v114, s[98:99]
	s_nop 0
	global_load_dwordx4 v[124:127], v120, s[98:99]
	s_nop 0
	global_load_dwordx4 v[120:123], v122, s[98:99]

.LBB0_1105:
	s_or_b64 exec, exec, s[4:5]
	v_lshlrev_b32_e32 v186, 16, v148
	v_and_b32_e32 v187, 0xffff0000, v148
	v_lshlrev_b32_e32 v188, 16, v149
	v_and_b32_e32 v189, 0xffff0000, v149
	v_lshlrev_b32_e32 v190, 16, v150
	v_and_b32_e32 v191, 0xffff0000, v150
	v_lshlrev_b32_e32 v192, 16, v151
	v_and_b32_e32 v193, 0xffff0000, v151
	v_lshlrev_b32_e32 v148, 16, v144
	v_and_b32_e32 v149, 0xffff0000, v144
	v_lshlrev_b32_e32 v144, 16, v145
	v_and_b32_e32 v145, 0xffff0000, v145
	v_lshlrev_b32_e32 v150, 16, v146
	v_and_b32_e32 v151, 0xffff0000, v146
	v_lshlrev_b32_e32 v146, 16, v147
	v_and_b32_e32 v147, 0xffff0000, v147
	s_waitcnt vmcnt(15)
	v_cvt_pk_f32_fp8_sdwa v[202:203], v0 src0_sel:WORD_1
	v_cvt_pk_f32_fp8_e32 v[204:205], v0
	v_cvt_pk_f32_fp8_e32 v[206:207], v1
	v_cvt_pk_f32_fp8_sdwa v[208:209], v1 src0_sel:WORD_1
	v_pk_mul_f32 v[202:203], v[202:203], v[188:189]
	v_cvt_pk_f32_fp8_sdwa v[212:213], v3 src0_sel:WORD_1
	v_pk_fma_f32 v[202:203], v[204:205], v[186:187], v[202:203]
	v_cvt_pk_f32_fp8_e32 v[204:205], v2
	v_pk_fma_f32 v[202:203], v[206:207], v[190:191], v[202:203]
	v_cvt_pk_f32_fp8_sdwa v[206:207], v2 src0_sel:WORD_1
	v_pk_fma_f32 v[202:203], v[208:209], v[192:193], v[202:203]
	v_cvt_pk_f32_fp8_e32 v[208:209], v3
	v_pk_fma_f32 v[202:203], v[204:205], v[148:149], v[202:203]
	s_waitcnt vmcnt(14)
	v_cvt_pk_f32_fp8_e32 v[204:205], v4
	v_pk_fma_f32 v[202:203], v[206:207], v[144:145], v[202:203]
	v_cvt_pk_f32_fp8_e32 v[206:207], v5
	v_pk_fma_f32 v[202:203], v[208:209], v[150:151], v[202:203]
	v_cvt_pk_f32_fp8_sdwa v[208:209], v5 src0_sel:WORD_1
	v_pk_fma_f32 v[202:203], v[212:213], v[146:147], v[202:203]
	v_cvt_pk_f32_fp8_sdwa v[212:213], v7 src0_sel:WORD_1
	v_add_f32_e32 v169, v202, v203
	v_cvt_pk_f32_fp8_sdwa v[202:203], v4 src0_sel:WORD_1
	s_mov_b64 s[40:41], -1
	v_add_f32_dpp v169, v169, v169 quad_perm:[1,0,3,2] row_mask:0xf bank_mask:0xf bound_ctrl:1
	v_pk_mul_f32 v[202:203], v[202:203], v[188:189]
	s_nop 0
	v_pk_fma_f32 v[202:203], v[204:205], v[186:187], v[202:203]
	v_cvt_pk_f32_fp8_e32 v[204:205], v6
	v_pk_fma_f32 v[202:203], v[206:207], v[190:191], v[202:203]
	v_cvt_pk_f32_fp8_sdwa v[206:207], v6 src0_sel:WORD_1
	v_pk_fma_f32 v[202:203], v[208:209], v[192:193], v[202:203]
	v_cvt_pk_f32_fp8_e32 v[208:209], v7
	v_pk_fma_f32 v[202:203], v[204:205], v[148:149], v[202:203]
	s_waitcnt vmcnt(13)
	v_cvt_pk_f32_fp8_e32 v[204:205], v8
	v_pk_fma_f32 v[202:203], v[206:207], v[144:145], v[202:203]
	v_cvt_pk_f32_fp8_e32 v[206:207], v9
	v_pk_fma_f32 v[202:203], v[208:209], v[150:151], v[202:203]
	v_cvt_pk_f32_fp8_sdwa v[208:209], v9 src0_sel:WORD_1
	v_pk_fma_f32 v[202:203], v[212:213], v[146:147], v[202:203]
	v_cvt_pk_f32_fp8_sdwa v[212:213], v11 src0_sel:WORD_1
	v_add_f32_e32 v173, v202, v203
	v_cvt_pk_f32_fp8_sdwa v[202:203], v8 src0_sel:WORD_1
	v_add_f32_dpp v169, v169, v169 quad_perm:[2,3,0,1] row_mask:0xf bank_mask:0xf bound_ctrl:1
	v_add_f32_dpp v173, v173, v173 quad_perm:[1,0,3,2] row_mask:0xf bank_mask:0xf bound_ctrl:1
	v_pk_mul_f32 v[202:203], v[202:203], v[188:189]
	s_nop 0
	v_pk_fma_f32 v[202:203], v[204:205], v[186:187], v[202:203]
	v_cvt_pk_f32_fp8_e32 v[204:205], v10
	v_pk_fma_f32 v[202:203], v[206:207], v[190:191], v[202:203]
	v_cvt_pk_f32_fp8_sdwa v[206:207], v10 src0_sel:WORD_1
	v_pk_fma_f32 v[202:203], v[208:209], v[192:193], v[202:203]
	v_cvt_pk_f32_fp8_e32 v[208:209], v11
	v_pk_fma_f32 v[202:203], v[204:205], v[148:149], v[202:203]
	v_add_f32_dpp v169, v169, v169 row_half_mirror row_mask:0xf bank_mask:0xf bound_ctrl:1
	v_pk_fma_f32 v[202:203], v[206:207], v[144:145], v[202:203]
	v_add_f32_dpp v173, v173, v173 quad_perm:[2,3,0,1] row_mask:0xf bank_mask:0xf bound_ctrl:1
	v_pk_fma_f32 v[202:203], v[208:209], v[150:151], v[202:203]
	v_cndmask_b32_e32 v169, 0, v169, vcc
	v_add_f32_dpp v173, v173, v173 row_half_mirror row_mask:0xf bank_mask:0xf bound_ctrl:1
	v_pk_fma_f32 v[202:203], v[212:213], v[146:147], v[202:203]
	v_cndmask_b32_e64 v169, v169, v173, s[6:7]
	v_add_f32_e32 v173, v202, v203
	s_waitcnt vmcnt(12)
	v_cvt_pk_f32_fp8_sdwa v[202:203], v12 src0_sel:WORD_1
	v_cvt_pk_f32_fp8_e32 v[204:205], v12
	v_cvt_pk_f32_fp8_e32 v[206:207], v13
	v_cvt_pk_f32_fp8_sdwa v[208:209], v13 src0_sel:WORD_1
	v_pk_mul_f32 v[202:203], v[202:203], v[188:189]
	v_cvt_pk_f32_fp8_sdwa v[212:213], v15 src0_sel:WORD_1
	v_pk_fma_f32 v[202:203], v[204:205], v[186:187], v[202:203]
	v_cvt_pk_f32_fp8_e32 v[204:205], v14
	v_pk_fma_f32 v[202:203], v[206:207], v[190:191], v[202:203]
	v_cvt_pk_f32_fp8_sdwa v[206:207], v14 src0_sel:WORD_1
	v_pk_fma_f32 v[202:203], v[208:209], v[192:193], v[202:203]
	v_cvt_pk_f32_fp8_e32 v[208:209], v15
	v_pk_fma_f32 v[202:203], v[204:205], v[148:149], v[202:203]
	v_add_f32_dpp v173, v173, v173 quad_perm:[1,0,3,2] row_mask:0xf bank_mask:0xf bound_ctrl:1
	v_pk_fma_f32 v[202:203], v[206:207], v[144:145], v[202:203]
	s_waitcnt vmcnt(11)
	v_cvt_pk_f32_fp8_e32 v[204:205], v16
	v_add_f32_dpp v173, v173, v173 quad_perm:[2,3,0,1] row_mask:0xf bank_mask:0xf bound_ctrl:1
	v_pk_fma_f32 v[202:203], v[208:209], v[150:151], v[202:203]
	v_cvt_pk_f32_fp8_e32 v[206:207], v17
	v_add_f32_dpp v173, v173, v173 row_half_mirror row_mask:0xf bank_mask:0xf bound_ctrl:1
	v_pk_fma_f32 v[202:203], v[212:213], v[146:147], v[202:203]
	v_cndmask_b32_e64 v169, v169, v173, s[8:9]
	v_add_f32_e32 v173, v202, v203
	v_cvt_pk_f32_fp8_sdwa v[202:203], v16 src0_sel:WORD_1
	v_cvt_pk_f32_fp8_sdwa v[208:209], v17 src0_sel:WORD_1
	v_cvt_pk_f32_fp8_sdwa v[212:213], v19 src0_sel:WORD_1
	v_add_f32_dpp v173, v173, v173 quad_perm:[1,0,3,2] row_mask:0xf bank_mask:0xf bound_ctrl:1
	v_pk_mul_f32 v[202:203], v[202:203], v[188:189]
	s_nop 0
	v_pk_fma_f32 v[202:203], v[204:205], v[186:187], v[202:203]
	v_cvt_pk_f32_fp8_e32 v[204:205], v18
	v_pk_fma_f32 v[202:203], v[206:207], v[190:191], v[202:203]
	v_cvt_pk_f32_fp8_sdwa v[206:207], v18 src0_sel:WORD_1
	v_pk_fma_f32 v[202:203], v[208:209], v[192:193], v[202:203]
	v_cvt_pk_f32_fp8_e32 v[208:209], v19
	v_pk_fma_f32 v[202:203], v[204:205], v[148:149], v[202:203]
	v_add_f32_dpp v173, v173, v173 quad_perm:[2,3,0,1] row_mask:0xf bank_mask:0xf bound_ctrl:1
	v_pk_fma_f32 v[202:203], v[206:207], v[144:145], v[202:203]
	s_waitcnt vmcnt(10)
	v_cvt_pk_f32_fp8_e32 v[204:205], v20
	v_pk_fma_f32 v[202:203], v[208:209], v[150:151], v[202:203]
	v_add_f32_dpp v173, v173, v173 row_half_mirror row_mask:0xf bank_mask:0xf bound_ctrl:1
	v_pk_fma_f32 v[202:203], v[212:213], v[146:147], v[202:203]
	v_cndmask_b32_e64 v169, v169, v173, s[16:17]
	v_add_f32_e32 v173, v202, v203
	v_cvt_pk_f32_fp8_sdwa v[202:203], v20 src0_sel:WORD_1
	v_cvt_pk_f32_fp8_e32 v[206:207], v21
	v_cvt_pk_f32_fp8_sdwa v[208:209], v21 src0_sel:WORD_1
	v_cvt_pk_f32_fp8_sdwa v[212:213], v23 src0_sel:WORD_1
	v_pk_mul_f32 v[202:203], v[202:203], v[188:189]
	v_add_f32_dpp v173, v173, v173 quad_perm:[1,0,3,2] row_mask:0xf bank_mask:0xf bound_ctrl:1
	v_pk_fma_f32 v[202:203], v[204:205], v[186:187], v[202:203]
	v_cvt_pk_f32_fp8_e32 v[204:205], v22
	v_pk_fma_f32 v[202:203], v[206:207], v[190:191], v[202:203]
	v_cvt_pk_f32_fp8_sdwa v[206:207], v22 src0_sel:WORD_1
	v_pk_fma_f32 v[202:203], v[208:209], v[192:193], v[202:203]
	v_cvt_pk_f32_fp8_e32 v[208:209], v23
	v_pk_fma_f32 v[202:203], v[204:205], v[148:149], v[202:203]
	v_add_f32_dpp v173, v173, v173 quad_perm:[2,3,0,1] row_mask:0xf bank_mask:0xf bound_ctrl:1
	v_pk_fma_f32 v[202:203], v[206:207], v[144:145], v[202:203]
	s_waitcnt vmcnt(9)
	v_cvt_pk_f32_fp8_e32 v[204:205], v24
	v_pk_fma_f32 v[202:203], v[208:209], v[150:151], v[202:203]
	v_add_f32_dpp v173, v173, v173 row_half_mirror row_mask:0xf bank_mask:0xf bound_ctrl:1
	v_pk_fma_f32 v[202:203], v[212:213], v[146:147], v[202:203]
	v_cndmask_b32_e64 v169, v169, v173, s[18:19]
	v_add_f32_e32 v173, v202, v203
	v_cvt_pk_f32_fp8_sdwa v[202:203], v24 src0_sel:WORD_1
	v_cvt_pk_f32_fp8_e32 v[206:207], v25
	v_cvt_pk_f32_fp8_sdwa v[208:209], v25 src0_sel:WORD_1
	v_cvt_pk_f32_fp8_sdwa v[212:213], v27 src0_sel:WORD_1
	v_pk_mul_f32 v[202:203], v[202:203], v[188:189]
	v_add_f32_dpp v173, v173, v173 quad_perm:[1,0,3,2] row_mask:0xf bank_mask:0xf bound_ctrl:1
	v_pk_fma_f32 v[202:203], v[204:205], v[186:187], v[202:203]
	v_cvt_pk_f32_fp8_e32 v[204:205], v26
	v_pk_fma_f32 v[202:203], v[206:207], v[190:191], v[202:203]
	v_cvt_pk_f32_fp8_sdwa v[206:207], v26 src0_sel:WORD_1
	v_pk_fma_f32 v[202:203], v[208:209], v[192:193], v[202:203]
	v_cvt_pk_f32_fp8_e32 v[208:209], v27
	v_pk_fma_f32 v[202:203], v[204:205], v[148:149], v[202:203]
	v_add_f32_dpp v173, v173, v173 quad_perm:[2,3,0,1] row_mask:0xf bank_mask:0xf bound_ctrl:1
	v_pk_fma_f32 v[202:203], v[206:207], v[144:145], v[202:203]
	s_waitcnt vmcnt(8)
	v_cvt_pk_f32_fp8_e32 v[204:205], v28
	v_pk_fma_f32 v[202:203], v[208:209], v[150:151], v[202:203]
	v_add_f32_dpp v173, v173, v173 row_half_mirror row_mask:0xf bank_mask:0xf bound_ctrl:1
	v_pk_fma_f32 v[202:203], v[212:213], v[146:147], v[202:203]
	v_cndmask_b32_e64 v169, v169, v173, s[20:21]
	v_add_f32_e32 v173, v202, v203
	v_cvt_pk_f32_fp8_sdwa v[202:203], v28 src0_sel:WORD_1
	v_cvt_pk_f32_fp8_e32 v[206:207], v29
	v_cvt_pk_f32_fp8_sdwa v[208:209], v29 src0_sel:WORD_1
	v_cvt_pk_f32_fp8_sdwa v[212:213], v31 src0_sel:WORD_1
	v_pk_mul_f32 v[202:203], v[202:203], v[188:189]
	v_add_f32_dpp v173, v173, v173 quad_perm:[1,0,3,2] row_mask:0xf bank_mask:0xf bound_ctrl:1
	v_pk_fma_f32 v[202:203], v[204:205], v[186:187], v[202:203]
	v_cvt_pk_f32_fp8_e32 v[204:205], v30
	v_pk_fma_f32 v[202:203], v[206:207], v[190:191], v[202:203]
	v_cvt_pk_f32_fp8_sdwa v[206:207], v30 src0_sel:WORD_1
	v_pk_fma_f32 v[202:203], v[208:209], v[192:193], v[202:203]
	v_cvt_pk_f32_fp8_e32 v[208:209], v31
	v_pk_fma_f32 v[202:203], v[204:205], v[148:149], v[202:203]
	v_add_f32_dpp v173, v173, v173 quad_perm:[2,3,0,1] row_mask:0xf bank_mask:0xf bound_ctrl:1
	v_pk_fma_f32 v[202:203], v[206:207], v[144:145], v[202:203]
	s_waitcnt vmcnt(7)
	v_cvt_pk_f32_fp8_e32 v[204:205], v32
	v_pk_fma_f32 v[202:203], v[208:209], v[150:151], v[202:203]
	v_add_f32_dpp v173, v173, v173 row_half_mirror row_mask:0xf bank_mask:0xf bound_ctrl:1
	v_pk_fma_f32 v[202:203], v[212:213], v[146:147], v[202:203]
	v_cndmask_b32_e64 v169, v169, v173, s[22:23]
	v_add_f32_e32 v173, v202, v203
	v_cvt_pk_f32_fp8_sdwa v[202:203], v32 src0_sel:WORD_1
	v_cvt_pk_f32_fp8_e32 v[206:207], v33
	v_cvt_pk_f32_fp8_sdwa v[208:209], v33 src0_sel:WORD_1
	v_cvt_pk_f32_fp8_sdwa v[212:213], v35 src0_sel:WORD_1
	v_pk_mul_f32 v[202:203], v[202:203], v[188:189]
	v_add_f32_dpp v173, v173, v173 quad_perm:[1,0,3,2] row_mask:0xf bank_mask:0xf bound_ctrl:1
	v_pk_fma_f32 v[202:203], v[204:205], v[186:187], v[202:203]
	v_cvt_pk_f32_fp8_e32 v[204:205], v34
	v_pk_fma_f32 v[202:203], v[206:207], v[190:191], v[202:203]
	v_cvt_pk_f32_fp8_sdwa v[206:207], v34 src0_sel:WORD_1
	v_pk_fma_f32 v[202:203], v[208:209], v[192:193], v[202:203]
	v_cvt_pk_f32_fp8_e32 v[208:209], v35
	v_pk_fma_f32 v[202:203], v[204:205], v[148:149], v[202:203]
	v_add_f32_dpp v173, v173, v173 quad_perm:[2,3,0,1] row_mask:0xf bank_mask:0xf bound_ctrl:1
	v_pk_fma_f32 v[202:203], v[206:207], v[144:145], v[202:203]
	s_waitcnt vmcnt(6)
	v_cvt_pk_f32_fp8_e32 v[204:205], v36
	v_pk_fma_f32 v[202:203], v[208:209], v[150:151], v[202:203]
	v_add_f32_dpp v173, v173, v173 row_half_mirror row_mask:0xf bank_mask:0xf bound_ctrl:1
	v_pk_fma_f32 v[202:203], v[212:213], v[146:147], v[202:203]
	v_cndmask_b32_e64 v173, v169, v173, s[24:25]
	v_add_f32_e32 v169, v202, v203
	v_cvt_pk_f32_fp8_sdwa v[202:203], v36 src0_sel:WORD_1
	v_cvt_pk_f32_fp8_e32 v[206:207], v37
	v_cvt_pk_f32_fp8_sdwa v[208:209], v37 src0_sel:WORD_1
	v_cvt_pk_f32_fp8_sdwa v[212:213], v39 src0_sel:WORD_1
	v_pk_mul_f32 v[202:203], v[202:203], v[188:189]
	v_add_f32_dpp v169, v169, v169 quad_perm:[1,0,3,2] row_mask:0xf bank_mask:0xf bound_ctrl:1
	v_pk_fma_f32 v[202:203], v[204:205], v[186:187], v[202:203]
	v_cvt_pk_f32_fp8_e32 v[204:205], v38
	v_pk_fma_f32 v[202:203], v[206:207], v[190:191], v[202:203]
	v_cvt_pk_f32_fp8_sdwa v[206:207], v38 src0_sel:WORD_1
	v_pk_fma_f32 v[202:203], v[208:209], v[192:193], v[202:203]
	v_cvt_pk_f32_fp8_e32 v[208:209], v39
	v_pk_fma_f32 v[202:203], v[204:205], v[148:149], v[202:203]
	s_waitcnt vmcnt(5)
	v_cvt_pk_f32_fp8_e32 v[204:205], v40
	v_pk_fma_f32 v[202:203], v[206:207], v[144:145], v[202:203]
	v_cvt_pk_f32_fp8_e32 v[206:207], v41
	v_pk_fma_f32 v[202:203], v[208:209], v[150:151], v[202:203]
	v_cvt_pk_f32_fp8_sdwa v[208:209], v41 src0_sel:WORD_1
	v_pk_fma_f32 v[202:203], v[212:213], v[146:147], v[202:203]
	v_cvt_pk_f32_fp8_sdwa v[212:213], v43 src0_sel:WORD_1
	v_add_f32_e32 v183, v202, v203
	v_cvt_pk_f32_fp8_sdwa v[202:203], v40 src0_sel:WORD_1
	v_add_f32_dpp v169, v169, v169 quad_perm:[2,3,0,1] row_mask:0xf bank_mask:0xf bound_ctrl:1
	v_add_f32_dpp v183, v183, v183 quad_perm:[1,0,3,2] row_mask:0xf bank_mask:0xf bound_ctrl:1
	v_pk_mul_f32 v[202:203], v[202:203], v[188:189]
	s_nop 0
	v_pk_fma_f32 v[202:203], v[204:205], v[186:187], v[202:203]
	v_cvt_pk_f32_fp8_e32 v[204:205], v42
	v_pk_fma_f32 v[202:203], v[206:207], v[190:191], v[202:203]
	v_cvt_pk_f32_fp8_sdwa v[206:207], v42 src0_sel:WORD_1
	v_pk_fma_f32 v[202:203], v[208:209], v[192:193], v[202:203]
	v_cvt_pk_f32_fp8_e32 v[208:209], v43
	v_pk_fma_f32 v[202:203], v[204:205], v[148:149], v[202:203]
	v_add_f32_dpp v169, v169, v169 row_half_mirror row_mask:0xf bank_mask:0xf bound_ctrl:1
	v_pk_fma_f32 v[202:203], v[206:207], v[144:145], v[202:203]
	v_add_f32_dpp v183, v183, v183 quad_perm:[2,3,0,1] row_mask:0xf bank_mask:0xf bound_ctrl:1
	v_pk_fma_f32 v[202:203], v[208:209], v[150:151], v[202:203]
	v_cndmask_b32_e32 v169, 0, v169, vcc
	v_add_f32_dpp v183, v183, v183 row_half_mirror row_mask:0xf bank_mask:0xf bound_ctrl:1
	v_pk_fma_f32 v[202:203], v[212:213], v[146:147], v[202:203]
	v_cndmask_b32_e64 v169, v169, v183, s[6:7]
	v_add_f32_e32 v183, v202, v203
	s_waitcnt vmcnt(4)
	v_cvt_pk_f32_fp8_sdwa v[202:203], v44 src0_sel:WORD_1
	v_cvt_pk_f32_fp8_e32 v[204:205], v44
	v_cvt_pk_f32_fp8_e32 v[206:207], v45
	v_cvt_pk_f32_fp8_sdwa v[208:209], v45 src0_sel:WORD_1
	v_pk_mul_f32 v[202:203], v[202:203], v[188:189]
	v_cvt_pk_f32_fp8_sdwa v[212:213], v47 src0_sel:WORD_1
	v_pk_fma_f32 v[202:203], v[204:205], v[186:187], v[202:203]
	v_cvt_pk_f32_fp8_e32 v[204:205], v46
	v_pk_fma_f32 v[202:203], v[206:207], v[190:191], v[202:203]
	v_cvt_pk_f32_fp8_sdwa v[206:207], v46 src0_sel:WORD_1
	v_pk_fma_f32 v[202:203], v[208:209], v[192:193], v[202:203]
	v_cvt_pk_f32_fp8_e32 v[208:209], v47
	v_pk_fma_f32 v[202:203], v[204:205], v[148:149], v[202:203]
	v_add_f32_dpp v183, v183, v183 quad_perm:[1,0,3,2] row_mask:0xf bank_mask:0xf bound_ctrl:1
	v_pk_fma_f32 v[202:203], v[206:207], v[144:145], v[202:203]
	s_waitcnt vmcnt(3)
	v_cvt_pk_f32_fp8_e32 v[204:205], v48
	v_add_f32_dpp v183, v183, v183 quad_perm:[2,3,0,1] row_mask:0xf bank_mask:0xf bound_ctrl:1
	v_pk_fma_f32 v[202:203], v[208:209], v[150:151], v[202:203]
	v_cvt_pk_f32_fp8_e32 v[206:207], v49
	v_add_f32_dpp v183, v183, v183 row_half_mirror row_mask:0xf bank_mask:0xf bound_ctrl:1
	v_pk_fma_f32 v[202:203], v[212:213], v[146:147], v[202:203]
	v_cndmask_b32_e64 v169, v169, v183, s[8:9]
	v_add_f32_e32 v183, v202, v203
	v_cvt_pk_f32_fp8_sdwa v[202:203], v48 src0_sel:WORD_1
	v_cvt_pk_f32_fp8_sdwa v[208:209], v49 src0_sel:WORD_1
	v_cvt_pk_f32_fp8_sdwa v[212:213], v51 src0_sel:WORD_1
	v_add_f32_dpp v183, v183, v183 quad_perm:[1,0,3,2] row_mask:0xf bank_mask:0xf bound_ctrl:1
	v_pk_mul_f32 v[202:203], v[202:203], v[188:189]
	s_nop 0
	v_pk_fma_f32 v[202:203], v[204:205], v[186:187], v[202:203]
	v_cvt_pk_f32_fp8_e32 v[204:205], v50
	v_pk_fma_f32 v[202:203], v[206:207], v[190:191], v[202:203]
	v_cvt_pk_f32_fp8_sdwa v[206:207], v50 src0_sel:WORD_1
	v_pk_fma_f32 v[202:203], v[208:209], v[192:193], v[202:203]
	v_cvt_pk_f32_fp8_e32 v[208:209], v51
	v_pk_fma_f32 v[202:203], v[204:205], v[148:149], v[202:203]
	v_add_f32_dpp v183, v183, v183 quad_perm:[2,3,0,1] row_mask:0xf bank_mask:0xf bound_ctrl:1
	v_pk_fma_f32 v[202:203], v[206:207], v[144:145], v[202:203]
	s_waitcnt vmcnt(2)
	v_cvt_pk_f32_fp8_e32 v[204:205], v52
	v_pk_fma_f32 v[202:203], v[208:209], v[150:151], v[202:203]
	v_add_f32_dpp v183, v183, v183 row_half_mirror row_mask:0xf bank_mask:0xf bound_ctrl:1
	v_pk_fma_f32 v[202:203], v[212:213], v[146:147], v[202:203]
	v_cndmask_b32_e64 v169, v169, v183, s[16:17]
	v_add_f32_e32 v183, v202, v203
	v_cvt_pk_f32_fp8_sdwa v[202:203], v52 src0_sel:WORD_1
	v_cvt_pk_f32_fp8_e32 v[206:207], v53
	v_cvt_pk_f32_fp8_sdwa v[208:209], v53 src0_sel:WORD_1
	v_cvt_pk_f32_fp8_sdwa v[212:213], v55 src0_sel:WORD_1
	v_pk_mul_f32 v[202:203], v[202:203], v[188:189]
	v_add_f32_dpp v183, v183, v183 quad_perm:[1,0,3,2] row_mask:0xf bank_mask:0xf bound_ctrl:1
	v_pk_fma_f32 v[202:203], v[204:205], v[186:187], v[202:203]
	v_cvt_pk_f32_fp8_e32 v[204:205], v54
	v_pk_fma_f32 v[202:203], v[206:207], v[190:191], v[202:203]
	v_cvt_pk_f32_fp8_sdwa v[206:207], v54 src0_sel:WORD_1
	v_pk_fma_f32 v[202:203], v[208:209], v[192:193], v[202:203]
	v_cvt_pk_f32_fp8_e32 v[208:209], v55
	v_pk_fma_f32 v[202:203], v[204:205], v[148:149], v[202:203]
	v_add_f32_dpp v183, v183, v183 quad_perm:[2,3,0,1] row_mask:0xf bank_mask:0xf bound_ctrl:1
	v_pk_fma_f32 v[202:203], v[206:207], v[144:145], v[202:203]
	s_waitcnt vmcnt(1)
	v_cvt_pk_f32_fp8_e32 v[204:205], v64
	v_pk_fma_f32 v[202:203], v[208:209], v[150:151], v[202:203]
	v_add_f32_dpp v183, v183, v183 row_half_mirror row_mask:0xf bank_mask:0xf bound_ctrl:1
	v_pk_fma_f32 v[202:203], v[212:213], v[146:147], v[202:203]
	v_cndmask_b32_e64 v169, v169, v183, s[18:19]
	v_add_f32_e32 v183, v202, v203
	v_cvt_pk_f32_fp8_sdwa v[202:203], v64 src0_sel:WORD_1
	v_cvt_pk_f32_fp8_e32 v[206:207], v65
	v_cvt_pk_f32_fp8_sdwa v[208:209], v65 src0_sel:WORD_1
	v_cvt_pk_f32_fp8_sdwa v[212:213], v67 src0_sel:WORD_1
	v_pk_mul_f32 v[202:203], v[202:203], v[188:189]
	v_add_f32_dpp v183, v183, v183 quad_perm:[1,0,3,2] row_mask:0xf bank_mask:0xf bound_ctrl:1
	v_pk_fma_f32 v[202:203], v[204:205], v[186:187], v[202:203]
	v_cvt_pk_f32_fp8_e32 v[204:205], v66
	v_pk_fma_f32 v[202:203], v[206:207], v[190:191], v[202:203]
	v_cvt_pk_f32_fp8_sdwa v[206:207], v66 src0_sel:WORD_1
	v_pk_fma_f32 v[202:203], v[208:209], v[192:193], v[202:203]
	v_cvt_pk_f32_fp8_e32 v[208:209], v67
	v_pk_fma_f32 v[202:203], v[204:205], v[148:149], v[202:203]
	v_add_f32_dpp v183, v183, v183 quad_perm:[2,3,0,1] row_mask:0xf bank_mask:0xf bound_ctrl:1
	v_pk_fma_f32 v[202:203], v[206:207], v[144:145], v[202:203]
	s_waitcnt vmcnt(0)
	v_cvt_pk_f32_fp8_e32 v[204:205], v68
	v_pk_fma_f32 v[202:203], v[208:209], v[150:151], v[202:203]
	v_add_f32_dpp v183, v183, v183 row_half_mirror row_mask:0xf bank_mask:0xf bound_ctrl:1
	v_pk_fma_f32 v[202:203], v[212:213], v[146:147], v[202:203]
	v_cndmask_b32_e64 v169, v169, v183, s[20:21]
	v_add_f32_e32 v183, v202, v203
	v_cvt_pk_f32_fp8_sdwa v[202:203], v68 src0_sel:WORD_1
	v_cvt_pk_f32_fp8_e32 v[206:207], v69
	v_cvt_pk_f32_fp8_sdwa v[208:209], v69 src0_sel:WORD_1
	v_add_f32_dpp v183, v183, v183 quad_perm:[1,0,3,2] row_mask:0xf bank_mask:0xf bound_ctrl:1
	v_pk_mul_f32 v[188:189], v[202:203], v[188:189]
	v_cvt_pk_f32_fp8_sdwa v[202:203], v71 src0_sel:WORD_1
	v_pk_fma_f32 v[186:187], v[204:205], v[186:187], v[188:189]
	v_cvt_pk_f32_fp8_e32 v[188:189], v70
	v_pk_fma_f32 v[186:187], v[206:207], v[190:191], v[186:187]
	v_cvt_pk_f32_fp8_sdwa v[190:191], v70 src0_sel:WORD_1
	v_pk_fma_f32 v[186:187], v[208:209], v[192:193], v[186:187]
	v_cvt_pk_f32_fp8_e32 v[192:193], v71
	v_pk_fma_f32 v[148:149], v[188:189], v[148:149], v[186:187]
	v_add_f32_dpp v183, v183, v183 quad_perm:[2,3,0,1] row_mask:0xf bank_mask:0xf bound_ctrl:1
	v_pk_fma_f32 v[144:145], v[190:191], v[144:145], v[148:149]
	s_nop 0
	v_pk_fma_f32 v[144:145], v[192:193], v[150:151], v[144:145]
	v_add_f32_dpp v183, v183, v183 row_half_mirror row_mask:0xf bank_mask:0xf bound_ctrl:1
	v_pk_fma_f32 v[144:145], v[202:203], v[146:147], v[144:145]
	v_cndmask_b32_e64 v169, v169, v183, s[22:23]
	v_add_f32_e32 v144, v144, v145
	s_nop 1
	v_add_f32_dpp v144, v144, v144 quad_perm:[1,0,3,2] row_mask:0xf bank_mask:0xf bound_ctrl:1
	s_nop 1
	v_add_f32_dpp v144, v144, v144 quad_perm:[2,3,0,1] row_mask:0xf bank_mask:0xf bound_ctrl:1
	s_nop 1
	v_add_f32_dpp v144, v144, v144 row_half_mirror row_mask:0xf bank_mask:0xf bound_ctrl:1
	v_cndmask_b32_e64 v146, v169, v144, s[24:25]
	v_ashrrev_i32_e32 v169, 31, v168
	v_lshlrev_b64 v[144:145], 9, v[168:169]
	v_lshl_add_u64 v[144:145], v[166:167], 0, v[144:145]
	global_store_dword v[144:145], v173, off
	global_store_dword v[144:145], v146, off offset:256
	s_and_saveexec_b64 s[4:5], s[26:27]
	s_cbranch_execz .LBB0_1100
	s_and_saveexec_b64 s[26:27], s[28:29]
	s_cbranch_execz .LBB0_1108
	ds_bpermute_b32 v0, v157, v159
	ds_bpermute_b32 v2, v194, v159
	ds_bpermute_b32 v8, v196, v159
	ds_bpermute_b32 v10, v197, v159
	ds_bpermute_b32 v16, v198, v159
	ds_bpermute_b32 v18, v199, v159
	ds_bpermute_b32 v24, v200, v159
	ds_bpermute_b32 v26, v201, v159
	ds_bpermute_b32 v32, v157, v161
	ds_bpermute_b32 v34, v194, v161
	ds_bpermute_b32 v40, v196, v161
	ds_bpermute_b32 v42, v197, v161
	ds_bpermute_b32 v48, v198, v161
	ds_bpermute_b32 v50, v199, v161
	ds_bpermute_b32 v64, v200, v161
	ds_bpermute_b32 v66, v201, v161
	s_waitcnt lgkmcnt(14)
	s_waitcnt lgkmcnt(13)
	s_waitcnt lgkmcnt(12)
	s_waitcnt lgkmcnt(11)
	s_waitcnt lgkmcnt(10)
	s_waitcnt lgkmcnt(9)
	s_waitcnt lgkmcnt(8)
	s_waitcnt lgkmcnt(7)
	s_waitcnt lgkmcnt(6)
	s_waitcnt lgkmcnt(5)
	s_waitcnt lgkmcnt(4)
	s_waitcnt lgkmcnt(3)
	s_waitcnt lgkmcnt(2)
	s_waitcnt lgkmcnt(1)
	s_waitcnt lgkmcnt(0)
	v_lshl_add_u32 v0, v0, 7, v255
	v_lshl_add_u32 v4, v2, 7, v255
	v_lshl_add_u32 v8, v8, 7, v255
	v_lshl_add_u32 v12, v10, 7, v255
	v_lshl_add_u32 v16, v16, 7, v255
	v_lshl_add_u32 v20, v18, 7, v255
	v_lshl_add_u32 v24, v24, 7, v255
	v_lshl_add_u32 v28, v26, 7, v255
	v_lshl_add_u32 v32, v32, 7, v255
	v_lshl_add_u32 v36, v34, 7, v255
	v_lshl_add_u32 v40, v40, 7, v255
	v_lshl_add_u32 v44, v42, 7, v255
	v_lshl_add_u32 v48, v48, 7, v255
	v_lshl_add_u32 v52, v50, 7, v255
	v_lshl_add_u32 v64, v64, 7, v255
	v_lshl_add_u32 v68, v66, 7, v255
	global_load_dwordx4 v[0:3], v0, s[98:99]
	s_nop 0
	global_load_dwordx4 v[4:7], v4, s[98:99]
	s_nop 0
	global_load_dwordx4 v[8:11], v8, s[98:99]
	s_nop 0
	global_load_dwordx4 v[12:15], v12, s[98:99]
	s_nop 0
	global_load_dwordx4 v[16:19], v16, s[98:99]
	s_nop 0
	global_load_dwordx4 v[20:23], v20, s[98:99]
	s_nop 0
	global_load_dwordx4 v[24:27], v24, s[98:99]
	s_nop 0
	global_load_dwordx4 v[28:31], v28, s[98:99]
	s_nop 0
	global_load_dwordx4 v[32:35], v32, s[98:99]
	s_nop 0
	global_load_dwordx4 v[36:39], v36, s[98:99]
	s_nop 0
	global_load_dwordx4 v[40:43], v40, s[98:99]
	s_nop 0
	global_load_dwordx4 v[44:47], v44, s[98:99]
	s_nop 0
	global_load_dwordx4 v[48:51], v48, s[98:99]
	s_nop 0
	global_load_dwordx4 v[52:55], v52, s[98:99]
	s_nop 0
	global_load_dwordx4 v[64:67], v64, s[98:99]
	s_nop 0
	global_load_dwordx4 v[68:71], v68, s[98:99]

.LBB0_1116:
	s_or_b64 exec, exec, s[0:1]
	s_barrier
	s_and_saveexec_b64 s[0:1], s[14:15]
	s_cbranch_execz .LBB0_1135
	s_lshl_b64 s[2:3], s[88:89], 12
	s_add_u32 s2, s94, s2
	v_mov_b32_e32 v161, 0
	s_addc_u32 s3, s95, s3
	v_lshl_add_u64 v[0:1], s[2:3], 0, v[160:161]
	s_mov_b64 s[2:3], 0xe1c0000
	s_waitcnt vmcnt(1)
	v_lshl_add_u64 v[36:37], v[0:1], 0, s[2:3]
	s_lshl_b64 s[4:5], s[96:97], 12
	s_mov_b64 s[8:9], 0
	s_mov_b64 s[14:15], 0xc180000
	s_mov_b32 s18, 0x378e98ab
	s_mov_b32 s19, 0x3b7cd369
	s_mov_b32 s20, 0xbcc618b2
	s_mov_b32 s21, 0x3dda74e4
	s_mov_b32 s22, 0x3f228afd
	s_mov_b32 s23, 0x3e03c728
	s_mov_b32 s24, 0xbfb8aa3b
	s_mov_b32 s25, 0x42ce8ed0
	s_mov_b32 s26, 0xc2b17218
	v_mov_b32_e32 v38, 0x3ba10414
	s_brev_b32 s27, -2
	s_mov_b64 s[16:17], 0x80ffff
	v_mov_b32_e32 v39, 0xb9c68948
	v_mov_b32_e32 v40, 0x7f800000
	v_lshrrev_b32_e32 v255, 6, v156
	s_nop 0
	v_readfirstlane_b32 s98, v255
	s_nop 3
	s_mul_i32 s98, s98, 0x2800
	v_subrev_u32_e32 v254, s94, v36
	s_add_u32 m0, s98, 0
	v_add_u32_e32 v255, 0xf9f40000, v254
	global_load_lds_dwordx4 v255, s[94:95]
	s_add_u32 m0, s98, 1024
	v_add_u32_e32 v255, 0xfbf80000, v254
	global_load_lds_dwordx4 v255, s[94:95]
	s_add_u32 m0, s98, 2048
	v_add_u32_e32 v255, 0xfdfc0000, v254
	global_load_lds_dwordx4 v255, s[94:95]
	s_add_u32 m0, s98, 3072
	v_add_u32_e32 v255, 0x2040000, v254
	global_load_lds_dwordx4 v255, s[94:95]
	s_add_u32 m0, s98, 4096
	v_mov_b32_e32 v255, v254
	global_load_lds_dwordx4 v255, s[94:95]
	s_add_u32 m0, s98, 5120
	v_add_u32_e32 v255, 0xa140000, v254
	global_load_lds_dwordx4 v255, s[94:95]
	s_add_u32 m0, s98, 6144
	v_add_u32_e32 v255, 0x4080000, v254
	global_load_lds_dwordx4 v255, s[94:95]
	s_add_u32 m0, s98, 7168
	v_add_u32_e32 v255, 0x60c0000, v254
	global_load_lds_dwordx4 v255, s[94:95]
	s_add_u32 m0, s98, 8192
	v_add_u32_e32 v255, 0x8100000, v254
	global_load_lds_dwordx4 v255, s[94:95]
	s_add_u32 m0, s98, 9216
	v_add_u32_e32 v255, 0xc180000, v254
	global_load_lds_dwordx4 v255, s[94:95]
	s_branch .LBB0_1119
.LBB0_1118:
	s_or_b64 exec, exec, s[2:3]
	v_bfi_b32 v9, s27, v13, v9
	v_mul_f32_e32 v5, 0.5, v5
	v_add_f32_e32 v9, 1.0, v9
	v_mul_f32_e32 v5, v5, v9
	v_mul_f32_e32 v1, v1, v5
	v_bfi_b32 v5, s27, v12, v8
	v_bfi_b32 v10, s27, v14, v10
	v_mul_f32_e32 v4, 0.5, v4
	v_add_f32_e32 v5, 1.0, v5
	v_mul_f32_e32 v6, 0.5, v6
	v_add_f32_e32 v10, 1.0, v10
	v_mul_f32_e32 v4, v4, v5
	v_mul_f32_e32 v6, v6, v10
	v_mul_f32_e32 v0, v0, v4
	v_bfi_b32 v4, s27, v15, v7
	v_mul_f32_e32 v2, v2, v6
	v_mul_f32_e32 v6, 0.5, v11
	v_add_f32_e32 v4, 1.0, v4
	v_mul_f32_e32 v4, v6, v4
	v_lshl_add_u64 v[184:185], v[184:185], 0, s[52:53]
	v_mul_f32_e32 v3, v3, v4
	v_cmp_lt_u64_e32 vcc, s[16:17], v[184:185]
	v_lshl_add_u64 v[16:17], v[36:37], 0, s[14:15]
	s_waitcnt vmcnt(11)
	v_mul_f32_e32 v2, v44, v2
	v_mul_f32_e32 v1, v43, v1
	v_mul_f32_e32 v0, v42, v0
	s_waitcnt vmcnt(10)
	v_mul_f32_e32 v3, v41, v3
	s_or_b64 s[8:9], vcc, s[8:9]
	v_lshl_add_u64 v[36:37], v[36:37], 0, s[4:5]
	global_store_dwordx4 v[16:17], v[0:3], off
	s_andn2_b64 exec, exec, s[8:9]
	s_cbranch_execz .LBB0_1135
.LBB0_1119:
	s_waitcnt vmcnt(0)
	v_mbcnt_lo_u32_b32 v255, -1, 0
	v_mbcnt_hi_u32_b32 v255, -1, v255
	v_lshlrev_b32_e32 v255, 4, v255
	v_add_u32_e32 v255, s98, v255
	ds_read_b128 v[4:7], v255 offset:0
	ds_read_b128 v[8:11], v255 offset:1024
	ds_read_b128 v[12:15], v255 offset:2048
	ds_read_b128 v[16:19], v255 offset:3072
	ds_read_b128 v[20:23], v255 offset:4096
	ds_read_b128 v[42:45], v255 offset:5120
	ds_read_b128 v[24:27], v255 offset:6144
	ds_read_b128 v[28:31], v255 offset:7168
	ds_read_b128 v[32:35], v255 offset:8192
	ds_read_b128 v[0:3], v255 offset:9216
	s_waitcnt lgkmcnt(0)
	v_ashrrev_i32_e32 v47, 31, v42
	v_mov_b32_e32 v46, v42
	v_ashrrev_i32_e32 v49, 31, v43
	v_mov_b32_e32 v48, v43
	v_lshlrev_b64 v[42:43], 2, v[46:47]
	v_lshlrev_b64 v[46:47], 2, v[48:49]
	v_lshl_add_u64 v[48:49], s[48:49], 0, v[42:43]
	v_lshl_add_u64 v[50:51], s[48:49], 0, v[46:47]
	v_ashrrev_i32_e32 v53, 31, v44
	v_mov_b32_e32 v52, v44
	v_ashrrev_i32_e32 v57, 31, v45
	v_mov_b32_e32 v56, v45
	v_lshlrev_b64 v[52:53], 2, v[52:53]
	v_lshlrev_b64 v[44:45], 2, v[56:57]
	v_lshl_add_u64 v[42:43], s[50:51], 0, v[42:43]
	v_lshl_add_u64 v[54:55], s[48:49], 0, v[52:53]
	v_lshl_add_u64 v[56:57], s[48:49], 0, v[44:45]
	v_lshl_add_u64 v[58:59], s[50:51], 0, v[46:47]
	v_lshl_add_u64 v[52:53], s[50:51], 0, v[52:53]
	v_lshl_add_u64 v[60:61], s[50:51], 0, v[44:45]
	global_load_dword v48, v[48:49], off
	s_nop 0
	global_load_dword v47, v[50:51], off
	global_load_dword v46, v[54:55], off
	global_load_dword v45, v[56:57], off
	s_nop 0
	global_load_dword v42, v[42:43], off
	s_nop 0
	global_load_dword v43, v[58:59], off
	global_load_dword v44, v[52:53], off
	global_load_dword v41, v[60:61], off
	v_add_u32_e32 v254, s4, v254
	s_add_u32 m0, s98, 0
	v_add_u32_e32 v255, 0xf9f40000, v254
	global_load_lds_dwordx4 v255, s[94:95]
	s_add_u32 m0, s98, 1024
	v_add_u32_e32 v255, 0xfbf80000, v254
	global_load_lds_dwordx4 v255, s[94:95]
	s_add_u32 m0, s98, 2048
	v_add_u32_e32 v255, 0xfdfc0000, v254
	global_load_lds_dwordx4 v255, s[94:95]
	s_add_u32 m0, s98, 3072
	v_add_u32_e32 v255, 0x2040000, v254
	global_load_lds_dwordx4 v255, s[94:95]
	s_add_u32 m0, s98, 4096
	v_mov_b32_e32 v255, v254
	global_load_lds_dwordx4 v255, s[94:95]
	s_add_u32 m0, s98, 5120
	v_add_u32_e32 v255, 0xa140000, v254
	global_load_lds_dwordx4 v255, s[94:95]
	s_add_u32 m0, s98, 6144
	v_add_u32_e32 v255, 0x4080000, v254
	global_load_lds_dwordx4 v255, s[94:95]
	s_add_u32 m0, s98, 7168
	v_add_u32_e32 v255, 0x60c0000, v254
	global_load_lds_dwordx4 v255, s[94:95]
	s_add_u32 m0, s98, 8192
	v_add_u32_e32 v255, 0x8100000, v254
	global_load_lds_dwordx4 v255, s[94:95]
	s_add_u32 m0, s98, 9216
	v_add_u32_e32 v255, 0xc180000, v254
	global_load_lds_dwordx4 v255, s[94:95]
	v_add_f32_e32 v4, 0, v4
	v_add_f32_e32 v4, v4, v8
	v_add_f32_e32 v4, v4, v12
	v_add_f32_e32 v4, v4, v20
	v_add_f32_e32 v4, v4, v16
	s_nop 0
	v_add_f32_e32 v4, v4, v24
	s_nop 0
	v_add_f32_e32 v4, v4, v28
	s_nop 0
	v_add_f32_e32 v4, v4, v32
	s_waitcnt vmcnt(17)
	v_mul_f32_e32 v4, v4, v48
	v_mul_f32_e32 v8, 0x3f3504f3, v4
	v_cmp_nlt_f32_e64 s[2:3], |v8|, 1.0
	s_and_saveexec_b64 s[6:7], s[2:3]
	s_xor_b64 s[2:3], exec, s[6:7]
	s_cbranch_execz .LBB0_1121
	v_fma_f32 v12, |v8|, s18, v39
	v_fma_f32 v12, |v8|, v12, s19
	v_fma_f32 v12, |v8|, v12, s20
	v_fma_f32 v12, |v8|, v12, s21
	v_fma_f32 v12, |v8|, v12, s22
	v_fma_f32 v12, |v8|, v12, s23
	v_fma_f32 v12, |v8|, v12, |v8|
	v_mul_f32_e32 v16, 0xbfb8aa3b, v12
	v_fma_f32 v20, v12, s24, -v16
	v_rndne_f32_e32 v24, v16
	v_fmac_f32_e32 v20, 0xb2a5705f, v12
	v_sub_f32_e32 v16, v16, v24
	v_add_f32_e32 v16, v16, v20
	v_cvt_i32_f32_e32 v20, v24
	v_exp_f32_e32 v16, v16
	v_cmp_nlt_f32_e32 vcc, s25, v12
	v_ldexp_f32 v16, v16, v20
	s_nop 0
	v_cndmask_b32_e32 v16, 0, v16, vcc
	v_cmp_ngt_f32_e32 vcc, s26, v12
	s_nop 1
	v_cndmask_b32_e32 v12, v40, v16, vcc
	v_sub_f32_e32 v12, 1.0, v12
.LBB0_1121:
	s_andn2_saveexec_b64 s[2:3], s[2:3]
	v_mul_f32_e32 v12, v8, v8
	v_fmamk_f32 v16, v12, 0xba1345e1, v38
	v_fmaak_f32 v16, v12, v16, 0xbcdac9b8
	v_fmaak_f32 v16, v12, v16, 0x3de703be
	v_fmaak_f32 v16, v12, v16, 0xbec09330
	v_fmaak_f32 v12, v12, v16, 0x3e0375d0
	v_fma_f32 v12, |v8|, v12, |v8|
	s_or_b64 exec, exec, s[2:3]
	v_add_f32_e32 v5, 0, v5
	v_add_f32_e32 v5, v5, v9
	v_add_f32_e32 v5, v5, v13
	v_add_f32_e32 v5, v5, v21
	v_add_f32_e32 v5, v5, v17
	v_add_f32_e32 v5, v5, v25
	v_add_f32_e32 v5, v5, v29
	v_add_f32_e32 v5, v5, v33
	s_waitcnt vmcnt(16)
	v_mul_f32_e32 v5, v5, v47
	v_mul_f32_e32 v9, 0x3f3504f3, v5
	v_cmp_nlt_f32_e64 s[2:3], |v9|, 1.0
	s_and_saveexec_b64 s[6:7], s[2:3]
	s_xor_b64 s[2:3], exec, s[6:7]
	s_cbranch_execz .LBB0_1125
	v_fma_f32 v13, |v9|, s18, v39
	v_fma_f32 v13, |v9|, v13, s19
	v_fma_f32 v13, |v9|, v13, s20
	v_fma_f32 v13, |v9|, v13, s21
	v_fma_f32 v13, |v9|, v13, s22
	v_fma_f32 v13, |v9|, v13, s23
	v_fma_f32 v13, |v9|, v13, |v9|
	v_mul_f32_e32 v16, 0xbfb8aa3b, v13
	v_fma_f32 v17, v13, s24, -v16
	v_rndne_f32_e32 v20, v16
	v_fmac_f32_e32 v17, 0xb2a5705f, v13
	v_sub_f32_e32 v16, v16, v20
	v_add_f32_e32 v16, v16, v17
	v_cvt_i32_f32_e32 v17, v20
	v_exp_f32_e32 v16, v16
	v_cmp_nlt_f32_e32 vcc, s25, v13
	v_ldexp_f32 v16, v16, v17
	s_nop 0
	v_cndmask_b32_e32 v16, 0, v16, vcc
	v_cmp_ngt_f32_e32 vcc, s26, v13
	s_nop 1
	v_cndmask_b32_e32 v13, v40, v16, vcc
	v_sub_f32_e32 v13, 1.0, v13
.LBB0_1125:
	s_andn2_saveexec_b64 s[2:3], s[2:3]
	v_mul_f32_e32 v13, v9, v9
	v_fmamk_f32 v16, v13, 0xba1345e1, v38
	v_fmaak_f32 v16, v13, v16, 0xbcdac9b8
	v_fmaak_f32 v16, v13, v16, 0x3de703be
	v_fmaak_f32 v16, v13, v16, 0xbec09330
	v_fmaak_f32 v13, v13, v16, 0x3e0375d0
	v_fma_f32 v13, |v9|, v13, |v9|
	s_or_b64 exec, exec, s[2:3]
	v_add_f32_e32 v6, 0, v6
	v_add_f32_e32 v6, v6, v10
	v_add_f32_e32 v6, v6, v14
	v_add_f32_e32 v6, v6, v22
	v_add_f32_e32 v6, v6, v18
	v_add_f32_e32 v6, v6, v26
	v_add_f32_e32 v6, v6, v30
	v_add_f32_e32 v6, v6, v34
	s_waitcnt vmcnt(15)
	v_mul_f32_e32 v6, v6, v46
	v_mul_f32_e32 v10, 0x3f3504f3, v6
	v_cmp_nlt_f32_e64 s[2:3], |v10|, 1.0
	s_and_saveexec_b64 s[6:7], s[2:3]
	s_xor_b64 s[2:3], exec, s[6:7]
	s_cbranch_execz .LBB0_1129
	v_fma_f32 v14, |v10|, s18, v39
	v_fma_f32 v14, |v10|, v14, s19
	v_fma_f32 v14, |v10|, v14, s20
	v_fma_f32 v14, |v10|, v14, s21
	v_fma_f32 v14, |v10|, v14, s22
	v_fma_f32 v14, |v10|, v14, s23
	v_fma_f32 v14, |v10|, v14, |v10|
	v_mul_f32_e32 v16, 0xbfb8aa3b, v14
	v_fma_f32 v17, v14, s24, -v16
	v_rndne_f32_e32 v18, v16
	v_fmac_f32_e32 v17, 0xb2a5705f, v14
	v_sub_f32_e32 v16, v16, v18
	v_add_f32_e32 v16, v16, v17
	v_cvt_i32_f32_e32 v17, v18
	v_exp_f32_e32 v16, v16
	v_cmp_nlt_f32_e32 vcc, s25, v14
	v_ldexp_f32 v16, v16, v17
	s_nop 0
	v_cndmask_b32_e32 v16, 0, v16, vcc
	v_cmp_ngt_f32_e32 vcc, s26, v14
	s_nop 1
	v_cndmask_b32_e32 v14, v40, v16, vcc
	v_sub_f32_e32 v14, 1.0, v14
.LBB0_1129:
	s_andn2_saveexec_b64 s[2:3], s[2:3]
	v_mul_f32_e32 v14, v10, v10
	v_fmamk_f32 v16, v14, 0xba1345e1, v38
	v_fmaak_f32 v16, v14, v16, 0xbcdac9b8
	v_fmaak_f32 v16, v14, v16, 0x3de703be
	v_fmaak_f32 v16, v14, v16, 0xbec09330
	v_fmaak_f32 v14, v14, v16, 0x3e0375d0
	v_fma_f32 v14, |v10|, v14, |v10|
	s_or_b64 exec, exec, s[2:3]
	v_add_f32_e32 v7, 0, v7
	v_add_f32_e32 v7, v7, v11
	v_add_f32_e32 v7, v7, v15
	v_add_f32_e32 v7, v7, v23
	v_add_f32_e32 v7, v7, v19
	v_add_f32_e32 v7, v7, v27
	v_add_f32_e32 v7, v7, v31
	v_add_f32_e32 v7, v7, v35
	s_waitcnt vmcnt(14)
	v_mul_f32_e32 v11, v7, v45
	v_mul_f32_e32 v7, 0x3f3504f3, v11
	v_cmp_nlt_f32_e64 s[2:3], |v7|, 1.0
	s_and_saveexec_b64 s[6:7], s[2:3]
	s_xor_b64 s[2:3], exec, s[6:7]
	s_cbranch_execz .LBB0_1133
	v_fma_f32 v15, |v7|, s18, v39
	v_fma_f32 v15, |v7|, v15, s19
	v_fma_f32 v15, |v7|, v15, s20
	v_fma_f32 v15, |v7|, v15, s21
	v_fma_f32 v15, |v7|, v15, s22
	v_fma_f32 v15, |v7|, v15, s23
	v_fma_f32 v15, |v7|, v15, |v7|
	v_mul_f32_e32 v16, 0xbfb8aa3b, v15
	v_fma_f32 v17, v15, s24, -v16
	v_rndne_f32_e32 v18, v16
	v_fmac_f32_e32 v17, 0xb2a5705f, v15
	v_sub_f32_e32 v16, v16, v18
	v_add_f32_e32 v16, v16, v17
	v_cvt_i32_f32_e32 v17, v18
	v_exp_f32_e32 v16, v16
	v_cmp_nlt_f32_e32 vcc, s25, v15
	v_ldexp_f32 v16, v16, v17
	s_nop 0
	v_cndmask_b32_e32 v16, 0, v16, vcc
	v_cmp_ngt_f32_e32 vcc, s26, v15
	s_nop 1
	v_cndmask_b32_e32 v15, v40, v16, vcc
	v_sub_f32_e32 v15, 1.0, v15

.LBB0_1141:
	s_or_b64 exec, exec, s[0:1]
	s_barrier
	s_and_saveexec_b64 s[0:1], s[12:13]
	s_cbranch_execz .LBB0_1160
	v_lshlrev_b64 v[0:1], 9, v[174:175]
	v_mov_b32_e32 v173, 0
	v_lshl_add_u64 v[2:3], s[38:39], 0, v[0:1]
	s_waitcnt vmcnt(1)
	v_or_b32_e32 v4, 0x100, v0
	s_waitcnt vmcnt(0)
	v_mov_b32_e32 v5, v1
	v_lshl_add_u64 v[0:1], s[36:37], 0, v[0:1]
	v_lshl_add_u64 v[128:129], s[38:39], 0, v[172:173]
	v_lshl_add_u64 v[0:1], v[0:1], 0, v[172:173]
	v_lshl_add_u64 v[130:131], s[36:37], 0, v[172:173]
	v_lshl_add_u64 v[2:3], v[2:3], 0, v[172:173]
	v_lshl_add_u64 v[6:7], v[128:129], 0, v[4:5]
	v_lshl_add_u64 v[4:5], v[130:131], 0, v[4:5]
	global_load_dword v144, v[0:1], off
	global_load_dword v146, v[4:5], off
	global_load_dword v145, v[2:3], off
	global_load_dword v147, v[6:7], off
	v_readlane_b32 s2, v252, 27
	s_lshl_b32 s2, s2, 7
	v_lshlrev_b64 v[0:1], 12, v[174:175]
	v_or3_b32 v2, v171, s2, v170
	v_lshl_add_u64 v[0:1], s[92:93], 0, v[0:1]
	v_mov_b32_e32 v61, v173
	v_lshlrev_b32_e32 v60, 2, v2
	v_mbcnt_hi_u32_b32 v62, -1, v155
	v_lshl_add_u64 v[0:1], v[0:1], 0, v[60:61]
	s_mov_b32 s18, 0xffff0000
	v_and_or_b32 v4, v62, 64, v210
	global_load_dwordx2 v[140:141], v[0:1], off
	v_lshlrev_b32_e32 v148, 2, v4
	v_mov_b32_e32 v3, v173
	v_mov_b32_e32 v5, v173
	v_mov_b32_e32 v7, v173
	v_mov_b32_e32 v9, v173
	v_mov_b32_e32 v11, v173
	v_mov_b32_e32 v13, v173
	v_mov_b32_e32 v15, v173
	v_mov_b32_e32 v17, v173
	v_mov_b32_e32 v19, v173
	v_mov_b32_e32 v21, v173
	s_mov_b32 s19, 0x10200
	v_cmp_gt_i32_e32 vcc, s19, v176
	s_waitcnt vmcnt(4)
	v_cvt_pk_bf16_f32 v0, v173, v144
	s_waitcnt vmcnt(3)
	v_cvt_pk_bf16_f32 v1, v173, v146
	v_and_b32_e32 v255, 7, v156
	v_lshlrev_b32_e32 v255, 4, v255
	v_readfirstlane_b32 s98, v180
	v_readfirstlane_b32 s99, v181
	s_mov_b32 s100, 0x7fff80
	s_waitcnt vmcnt(2)
	v_and_or_b32 v0, v0, s18, v145
	s_waitcnt vmcnt(1)
	v_and_or_b32 v63, v1, s18, v147
	ds_bpermute_b32 v149, v148, v0
	ds_bpermute_b32 v150, v148, v0 offset:32
	ds_bpermute_b32 v151, v148, v0 offset:64
	ds_bpermute_b32 v155, v148, v0 offset:96
	ds_bpermute_b32 v157, v148, v0 offset:128
	ds_bpermute_b32 v159, v148, v0 offset:160
	ds_bpermute_b32 v160, v148, v0 offset:192
	ds_bpermute_b32 v161, v148, v0 offset:224
	ds_bpermute_b32 v162, v148, v63
	ds_bpermute_b32 v163, v148, v63 offset:32
	ds_bpermute_b32 v164, v148, v63 offset:64
	ds_bpermute_b32 v165, v148, v63 offset:96
	s_waitcnt lgkmcnt(11)
	v_lshlrev_b32_e32 v0, 7, v149
	s_waitcnt lgkmcnt(10)
	v_lshlrev_b32_e32 v1, 7, v150
	s_waitcnt lgkmcnt(9)
	v_lshlrev_b32_e32 v6, 7, v151
	s_waitcnt lgkmcnt(8)
	v_lshlrev_b32_e32 v8, 7, v155
	s_waitcnt lgkmcnt(7)
	v_lshlrev_b32_e32 v10, 7, v157
	s_waitcnt lgkmcnt(6)
	v_lshlrev_b32_e32 v12, 7, v159
	s_waitcnt lgkmcnt(5)
	v_lshlrev_b32_e32 v14, 7, v160
	s_waitcnt lgkmcnt(4)
	v_lshlrev_b32_e32 v16, 7, v161
	s_waitcnt lgkmcnt(3)
	v_lshlrev_b32_e32 v18, 7, v162
	s_waitcnt lgkmcnt(2)
	v_lshlrev_b32_e32 v20, 7, v163
	v_and_or_b32 v40, v0, s100, v255
	ds_bpermute_b32 v185, v148, v63 offset:128
	v_and_or_b32 v42, v1, s100, v255
	v_and_or_b32 v44, v6, s100, v255
	v_and_or_b32 v46, v8, s100, v255
	v_and_or_b32 v48, v10, s100, v255
	v_and_or_b32 v50, v12, s100, v255
	v_and_or_b32 v52, v14, s100, v255
	v_and_or_b32 v54, v16, s100, v255
	v_and_or_b32 v56, v18, s100, v255
	v_and_or_b32 v58, v20, s100, v255
	global_load_dwordx4 v[0:3], v40, s[98:99]
	global_load_dwordx4 v[4:7], v42, s[98:99]
	global_load_dwordx4 v[8:11], v44, s[98:99]
	global_load_dwordx4 v[12:15], v46, s[98:99]
	global_load_dwordx4 v[16:19], v48, s[98:99]
	global_load_dwordx4 v[20:23], v50, s[98:99]
	global_load_dwordx4 v[24:27], v52, s[98:99]
	global_load_dwordx4 v[28:31], v54, s[98:99]
	global_load_dwordx4 v[32:35], v56, s[98:99]
	global_load_dwordx4 v[36:39], v58, s[98:99]
	s_waitcnt lgkmcnt(2)
	v_lshlrev_b32_e32 v40, 7, v164
	v_mov_b32_e32 v41, v173
	ds_bpermute_b32 v186, v148, v63 offset:160
	v_and_or_b32 v48, v40, s100, v255
	s_waitcnt lgkmcnt(2)
	v_lshlrev_b32_e32 v40, 7, v165
	ds_bpermute_b32 v187, v148, v63 offset:192
	v_and_or_b32 v50, v40, s100, v255
	global_load_dwordx4 v[40:43], v48, s[98:99]
	global_load_dwordx4 v[44:47], v50, s[98:99]
	s_waitcnt lgkmcnt(2)
	v_lshlrev_b32_e32 v48, 7, v185
	v_mov_b32_e32 v49, v173
	ds_bpermute_b32 v188, v148, v63 offset:224
	v_and_or_b32 v56, v48, s100, v255
	s_waitcnt lgkmcnt(2)
	v_lshlrev_b32_e32 v48, 7, v186
	v_and_or_b32 v58, v48, s100, v255
	global_load_dwordx4 v[48:51], v56, s[98:99]
	global_load_dwordx4 v[52:55], v58, s[98:99]
	s_waitcnt lgkmcnt(1)
	v_lshlrev_b32_e32 v56, 7, v187
	v_mov_b32_e32 v57, v173
	v_and_or_b32 v64, v56, s100, v255
	s_waitcnt lgkmcnt(0)
	v_lshlrev_b32_e32 v56, 7, v188
	v_and_or_b32 v66, v56, s100, v255
	global_load_dwordx4 v[56:59], v64, s[98:99]
	global_load_dwordx4 v[68:71], v66, s[98:99]
	s_and_saveexec_b64 s[2:3], vcc
	s_cbranch_execz .LBB0_1144
	v_ashrrev_i32_e32 v177, 31, v176
	v_lshlrev_b64 v[64:65], 9, v[176:177]
	v_lshl_add_u64 v[66:67], s[38:39], 0, v[64:65]
	v_or_b32_e32 v72, 0x100, v64
	v_mov_b32_e32 v73, v65
	v_lshl_add_u64 v[64:65], s[36:37], 0, v[64:65]
	v_lshl_add_u64 v[66:67], v[66:67], 0, v[172:173]
	v_lshl_add_u64 v[64:65], v[64:65], 0, v[172:173]
	v_lshl_add_u64 v[74:75], v[128:129], 0, v[72:73]
	v_lshl_add_u64 v[72:73], v[130:131], 0, v[72:73]
	global_load_dword v166, v[66:67], off
	global_load_dword v167, v[74:75], off
	global_load_dword v168, v[64:65], off
	global_load_dword v169, v[72:73], off
	v_lshlrev_b64 v[64:65], 12, v[176:177]
	v_lshl_add_u64 v[64:65], s[92:93], 0, v[64:65]
	v_lshl_add_u64 v[64:65], v[64:65], 0, v[60:61]
	global_load_dwordx2 v[134:135], v[64:65], off

.LBB0_1147:
	v_add_u32_e32 v136, s68, v174
	v_cmp_gt_i32_e64 s[8:9], s19, v136
	s_and_saveexec_b64 s[12:13], s[8:9]
	s_cbranch_execz .LBB0_1149
	s_waitcnt vmcnt(2)
	v_cvt_pk_bf16_f32 v60, v173, v168
	s_nop 0
	v_and_or_b32 v84, v60, s18, v166
	ds_bpermute_b32 v189, v148, v84
	ds_bpermute_b32 v190, v170, v84
	ds_bpermute_b32 v191, v171, v84
	ds_bpermute_b32 v192, v176, v84
	s_waitcnt vmcnt(1)
	v_cvt_pk_bf16_f32 v60, v173, v169
	ds_bpermute_b32 v193, v177, v84
	v_and_or_b32 v116, v60, s18, v167
	s_waitcnt lgkmcnt(4)
	v_lshlrev_b32_e32 v60, 7, v189
	ds_bpermute_b32 v194, v178, v84
	s_waitcnt lgkmcnt(4)
	v_lshlrev_b32_e32 v62, 7, v190
	ds_bpermute_b32 v195, v179, v84
	v_and_or_b32 v60, v60, s100, v255
	s_waitcnt lgkmcnt(4)
	v_lshlrev_b32_e32 v72, 7, v191
	ds_bpermute_b32 v196, v182, v84
	v_and_or_b32 v62, v62, s100, v255
	s_waitcnt lgkmcnt(4)
	v_lshlrev_b32_e32 v74, 7, v192
	ds_bpermute_b32 v197, v148, v116
	v_and_or_b32 v72, v72, s100, v255
	s_waitcnt lgkmcnt(4)
	v_lshlrev_b32_e32 v80, 7, v193
	ds_bpermute_b32 v198, v170, v116
	v_and_or_b32 v74, v74, s100, v255
	s_waitcnt lgkmcnt(4)
	v_lshlrev_b32_e32 v82, 7, v194
	ds_bpermute_b32 v199, v171, v116
	v_and_or_b32 v80, v80, s100, v255
	s_waitcnt lgkmcnt(4)
	v_lshlrev_b32_e32 v88, 7, v195
	ds_bpermute_b32 v200, v176, v116
	v_and_or_b32 v82, v82, s100, v255
	s_waitcnt lgkmcnt(4)
	v_lshlrev_b32_e32 v90, 7, v196
	ds_bpermute_b32 v201, v177, v116
	v_and_or_b32 v88, v88, s100, v255
	s_waitcnt lgkmcnt(4)
	v_lshlrev_b32_e32 v96, 7, v197
	ds_bpermute_b32 v202, v178, v116
	v_and_or_b32 v90, v90, s100, v255
	s_waitcnt lgkmcnt(4)
	v_lshlrev_b32_e32 v98, 7, v198
	ds_bpermute_b32 v203, v179, v116
	v_and_or_b32 v96, v96, s100, v255
	s_waitcnt lgkmcnt(4)
	v_lshlrev_b32_e32 v104, 7, v199
	ds_bpermute_b32 v204, v182, v116
	v_and_or_b32 v98, v98, s100, v255
	s_waitcnt lgkmcnt(4)
	v_lshlrev_b32_e32 v106, 7, v200
	v_and_or_b32 v104, v104, s100, v255
	s_waitcnt lgkmcnt(3)
	v_lshlrev_b32_e32 v112, 7, v201
	v_and_or_b32 v106, v106, s100, v255
	s_waitcnt lgkmcnt(2)
	v_lshlrev_b32_e32 v114, 7, v202
	v_and_or_b32 v112, v112, s100, v255
	s_waitcnt lgkmcnt(1)
	v_lshlrev_b32_e32 v120, 7, v203
	v_and_or_b32 v114, v114, s100, v255
	s_waitcnt lgkmcnt(0)
	v_lshlrev_b32_e32 v122, 7, v204
	v_and_or_b32 v120, v120, s100, v255
	v_and_or_b32 v122, v122, s100, v255
	global_load_dwordx4 v[64:67], v60, s[98:99]
	s_nop 0
	global_load_dwordx4 v[60:63], v62, s[98:99]
	s_nop 0
	global_load_dwordx4 v[76:79], v72, s[98:99]
	s_nop 0
	global_load_dwordx4 v[72:75], v74, s[98:99]
	s_nop 0
	global_load_dwordx4 v[84:87], v80, s[98:99]
	s_nop 0
	global_load_dwordx4 v[80:83], v82, s[98:99]
	s_nop 0
	global_load_dwordx4 v[92:95], v88, s[98:99]
	s_nop 0
	global_load_dwordx4 v[88:91], v90, s[98:99]
	s_nop 0
	global_load_dwordx4 v[100:103], v96, s[98:99]
	s_nop 0
	global_load_dwordx4 v[96:99], v98, s[98:99]
	s_nop 0
	global_load_dwordx4 v[108:111], v104, s[98:99]
	s_nop 0
	global_load_dwordx4 v[104:107], v106, s[98:99]
	s_nop 0
	global_load_dwordx4 v[116:119], v112, s[98:99]
	s_nop 0
	global_load_dwordx4 v[112:115], v114, s[98:99]
	s_nop 0
	global_load_dwordx4 v[124:127], v120, s[98:99]
	s_nop 0
	global_load_dwordx4 v[120:123], v122, s[98:99]

.LBB0_1153:
	s_or_b64 exec, exec, s[14:15]
	s_mov_b64 s[16:17], -1
	s_and_saveexec_b64 s[14:15], s[8:9]
	s_cbranch_execz .LBB0_1146
	s_and_saveexec_b64 s[8:9], s[12:13]
	s_cbranch_execz .LBB0_1156
	v_cvt_pk_bf16_f32 v0, v173, v144
	s_nop 0
	v_and_or_b32 v18, v0, s18, v145
	ds_bpermute_b32 v149, v148, v18
	ds_bpermute_b32 v150, v170, v18
	ds_bpermute_b32 v151, v171, v18
	ds_bpermute_b32 v155, v176, v18
	v_cvt_pk_bf16_f32 v0, v173, v146
	ds_bpermute_b32 v157, v177, v18
	v_and_or_b32 v50, v0, s18, v147
	s_waitcnt lgkmcnt(4)
	v_lshlrev_b32_e32 v0, 7, v149
	ds_bpermute_b32 v159, v178, v18
	s_waitcnt lgkmcnt(4)
	v_lshlrev_b32_e32 v2, 7, v150
	ds_bpermute_b32 v160, v179, v18
	v_and_or_b32 v0, v0, s100, v255
	s_waitcnt lgkmcnt(4)
	v_lshlrev_b32_e32 v8, 7, v151
	ds_bpermute_b32 v161, v182, v18
	v_and_or_b32 v4, v2, s100, v255
	s_waitcnt lgkmcnt(4)
	v_lshlrev_b32_e32 v10, 7, v155
	ds_bpermute_b32 v162, v148, v50
	v_and_or_b32 v8, v8, s100, v255
	s_waitcnt lgkmcnt(4)
	v_lshlrev_b32_e32 v16, 7, v157
	ds_bpermute_b32 v163, v170, v50
	v_and_or_b32 v12, v10, s100, v255
	s_waitcnt lgkmcnt(4)
	v_lshlrev_b32_e32 v19, 7, v159
	ds_bpermute_b32 v164, v171, v50
	v_and_or_b32 v16, v16, s100, v255
	s_waitcnt lgkmcnt(4)
	v_lshlrev_b32_e32 v24, 7, v160
	ds_bpermute_b32 v165, v176, v50
	v_and_or_b32 v20, v19, s100, v255
	s_waitcnt lgkmcnt(4)
	v_lshlrev_b32_e32 v26, 7, v161
	ds_bpermute_b32 v185, v177, v50
	v_and_or_b32 v24, v24, s100, v255
	s_waitcnt lgkmcnt(4)
	v_lshlrev_b32_e32 v32, 7, v162
	ds_bpermute_b32 v186, v178, v50
	v_and_or_b32 v28, v26, s100, v255
	s_waitcnt lgkmcnt(4)
	v_lshlrev_b32_e32 v34, 7, v163
	ds_bpermute_b32 v187, v179, v50
	v_and_or_b32 v32, v32, s100, v255
	s_waitcnt lgkmcnt(4)
	v_lshlrev_b32_e32 v40, 7, v164
	ds_bpermute_b32 v188, v182, v50
	v_and_or_b32 v36, v34, s100, v255
	s_waitcnt lgkmcnt(4)
	v_lshlrev_b32_e32 v42, 7, v165
	v_and_or_b32 v40, v40, s100, v255
	s_waitcnt lgkmcnt(3)
	v_lshlrev_b32_e32 v48, 7, v185
	v_and_or_b32 v44, v42, s100, v255
	s_waitcnt lgkmcnt(2)
	v_lshlrev_b32_e32 v51, 7, v186
	v_and_or_b32 v48, v48, s100, v255
	s_waitcnt lgkmcnt(1)
	v_lshlrev_b32_e32 v56, 7, v187
	v_and_or_b32 v52, v51, s100, v255
	s_waitcnt lgkmcnt(0)
	v_lshlrev_b32_e32 v58, 7, v188
	v_and_or_b32 v56, v56, s100, v255
	v_and_or_b32 v68, v58, s100, v255
	global_load_dwordx4 v[0:3], v0, s[98:99]
	s_nop 0
	global_load_dwordx4 v[4:7], v4, s[98:99]
	s_nop 0
	global_load_dwordx4 v[8:11], v8, s[98:99]
	s_nop 0
	global_load_dwordx4 v[12:15], v12, s[98:99]
	s_nop 0
	global_load_dwordx4 v[16:19], v16, s[98:99]
	s_nop 0
	global_load_dwordx4 v[20:23], v20, s[98:99]
	s_nop 0
	global_load_dwordx4 v[24:27], v24, s[98:99]
	s_nop 0
	global_load_dwordx4 v[28:31], v28, s[98:99]
	s_nop 0
	global_load_dwordx4 v[32:35], v32, s[98:99]
	s_nop 0
	global_load_dwordx4 v[36:39], v36, s[98:99]
	s_nop 0
	global_load_dwordx4 v[40:43], v40, s[98:99]
	s_nop 0
	global_load_dwordx4 v[44:47], v44, s[98:99]
	s_nop 0
	global_load_dwordx4 v[48:51], v48, s[98:99]
	s_nop 0
	global_load_dwordx4 v[52:55], v52, s[98:99]
	s_nop 0
	global_load_dwordx4 v[56:59], v56, s[98:99]
	s_nop 0
	global_load_dwordx4 v[68:71], v68, s[98:99]

	.amdhsa_kernel _Z6k_mega6Params
		.amdhsa_group_segment_fixed_size 0
		.amdhsa_private_segment_fixed_size 0
		.amdhsa_kernarg_size 560
		.amdhsa_user_sgpr_count 2
		.amdhsa_user_sgpr_dispatch_ptr 0
		.amdhsa_user_sgpr_queue_ptr 0
		.amdhsa_user_sgpr_kernarg_segment_ptr 1
		.amdhsa_user_sgpr_dispatch_id 0
		.amdhsa_user_sgpr_kernarg_preload_length 0
		.amdhsa_user_sgpr_kernarg_preload_offset 0
		.amdhsa_user_sgpr_private_segment_size 0
		.amdhsa_uses_dynamic_stack 0
		.amdhsa_enable_private_segment 0
		.amdhsa_system_sgpr_workgroup_id_x 1
		.amdhsa_system_sgpr_workgroup_id_y 0
		.amdhsa_system_sgpr_workgroup_id_z 0
		.amdhsa_system_sgpr_workgroup_info 0
		.amdhsa_system_vgpr_workitem_id 2
		.amdhsa_next_free_vgpr 256
		.amdhsa_next_free_sgpr 102
		.amdhsa_accum_offset 256
		.amdhsa_reserve_vcc 1
		.amdhsa_float_round_mode_32 0
		.amdhsa_float_round_mode_16_64 0
		.amdhsa_float_denorm_mode_32 3
		.amdhsa_float_denorm_mode_16_64 3
		.amdhsa_dx10_clamp 1
		.amdhsa_ieee_mode 1
		.amdhsa_fp16_overflow 0
		.amdhsa_tg_split 0
		.amdhsa_exception_fp_ieee_invalid_op 0
		.amdhsa_exception_fp_denorm_src 0
		.amdhsa_exception_fp_ieee_div_zero 0
		.amdhsa_exception_fp_ieee_overflow 0
		.amdhsa_exception_fp_ieee_underflow 0
		.amdhsa_exception_fp_ieee_inexact 0
		.amdhsa_exception_int_div_zero 0
	.end_amdhsa_kernel

amdhsa.kernels:
  - .agpr_count:     0
    .args:
      - .offset:         0
        .size:           304
        .value_kind:     by_value
      - .offset:         304
        .size:           4
        .value_kind:     hidden_block_count_x
      - .offset:         308
        .size:           4
        .value_kind:     hidden_block_count_y
      - .offset:         312
        .size:           4
        .value_kind:     hidden_block_count_z
      - .offset:         316
        .size:           2
        .value_kind:     hidden_group_size_x
      - .offset:         318
        .size:           2
        .value_kind:     hidden_group_size_y
      - .offset:         320
        .size:           2
        .value_kind:     hidden_group_size_z
      - .offset:         322
        .size:           2
        .value_kind:     hidden_remainder_x
      - .offset:         324
        .size:           2
        .value_kind:     hidden_remainder_y
      - .offset:         326
        .size:           2
        .value_kind:     hidden_remainder_z
      - .offset:         344
        .size:           8
        .value_kind:     hidden_global_offset_x
      - .offset:         352
        .size:           8
        .value_kind:     hidden_global_offset_y
      - .offset:         360
        .size:           8
        .value_kind:     hidden_global_offset_z
      - .offset:         368
        .size:           2
        .value_kind:     hidden_grid_dims
      - .offset:         392
        .size:           8
        .value_kind:     hidden_multigrid_sync_arg
      - .offset:         424
        .size:           4
        .value_kind:     hidden_dynamic_lds_size
    .group_segment_fixed_size: 0
    .kernarg_segment_align: 8
    .kernarg_segment_size: 560
    .language:       OpenCL C
    .language_version:
      - 2
      - 0
    .max_flat_workgroup_size: 256
    .name:           _Z6k_mega6Params
    .private_segment_fixed_size: 0
    .sgpr_count:     108
    .sgpr_spill_count: 136
    .symbol:         _Z6k_mega6Params.kd
    .uniform_work_group_size: 1
    .uses_dynamic_stack: false
    .vgpr_count:     256
    .vgpr_spill_count: 0
    .wavefront_size: 64
